# gelu-path LayerNorm statistic reductions (P3a) also use v_permlane swaps instead of ds_bpermute
# baseline (speedup 1.0000x reference)
.LBB0_567:
	s_waitcnt vmcnt(0)
	v_fmamk_f32 v184, v200, 0x3a800000, v228
	v_rsq_f32_e32 v184, v184
	s_cmp_eq_u32 s83, 4
	s_cselect_b64 s[10:11], -1, 0
	s_cmp_eq_u32 s83, 1
	s_cselect_b64 s[8:9], -1, 0
	v_pk_fma_f32 v[158:159], v[158:159], v[184:185], v[46:47] op_sel_hi:[1,0,1]
	v_pk_fma_f32 v[156:157], v[156:157], v[184:185], v[44:45] op_sel_hi:[1,0,1]
	v_pk_fma_f32 v[154:155], v[154:155], v[184:185], v[42:43] op_sel_hi:[1,0,1]
	v_pk_fma_f32 v[152:153], v[152:153], v[184:185], v[40:41] op_sel_hi:[1,0,1]
	v_pk_fma_f32 v[150:151], v[150:151], v[184:185], v[38:39] op_sel_hi:[1,0,1]
	v_pk_fma_f32 v[148:149], v[148:149], v[184:185], v[36:37] op_sel_hi:[1,0,1]
	v_pk_fma_f32 v[146:147], v[146:147], v[184:185], v[34:35] op_sel_hi:[1,0,1]
	v_pk_fma_f32 v[144:145], v[144:145], v[184:185], v[32:33] op_sel_hi:[1,0,1]
	v_cndmask_b32_e64 v184, 0, 1, s[8:9]
	s_mov_b64 s[94:95], -1
	s_and_b64 vcc, exec, s[92:93]
	v_cmp_ne_u32_e64 s[8:9], 1, v184
	s_cbranch_vccz .LBB0_573
	s_and_b64 vcc, exec, s[8:9]
	v_mov_b32_e32 v209, v159
	v_mov_b32_e32 v208, v158
	v_mov_b32_e32 v207, v157
	v_mov_b32_e32 v206, v156
	v_mov_b32_e32 v213, v155
	v_mov_b32_e32 v212, v154
	v_mov_b32_e32 v211, v153
	v_mov_b32_e32 v210, v152
	v_mov_b32_e32 v217, v151
	v_mov_b32_e32 v216, v150
	v_mov_b32_e32 v215, v149
	v_mov_b32_e32 v214, v148
	v_mov_b32_e32 v221, v147
	v_mov_b32_e32 v220, v146
	v_mov_b32_e32 v219, v145
	v_mov_b32_e32 v218, v144
	s_cbranch_vccnz .LBB0_572
	v_and_b32_e32 v201, 0x7fffffff, v157
	v_and_b32_e32 v200, 0x7fffffff, v156
	v_pk_fma_f32 v[200:201], v[200:201], s[68:69], 1.0 op_sel_hi:[1,0,0]
	v_pk_mul_f32 v[210:211], v[156:157], v[156:157]
	v_rcp_f32_e32 v206, v200
	v_rcp_f32_e32 v207, v201
	v_mov_b64_e32 v[200:201], s[72:73]
	v_pk_mul_f32 v[210:211], v[210:211], s[80:81] op_sel_hi:[1,0]
	v_cmp_gt_f32_e32 vcc, 0, v156
	v_pk_fma_f32 v[208:209], v[206:207], s[70:71], v[200:201] op_sel_hi:[1,0,0]
	v_exp_f32_e32 v210, v210
	v_pk_fma_f32 v[208:209], v[206:207], v[208:209], s[74:75] op_sel_hi:[1,1,0]
	v_exp_f32_e32 v211, v211
	v_pk_fma_f32 v[208:209], v[206:207], v[208:209], s[76:77] op_sel_hi:[1,1,0]
	v_pk_mul_f32 v[214:215], v[152:153], v[152:153]
	v_pk_fma_f32 v[208:209], v[206:207], v[208:209], s[78:79] op_sel_hi:[1,1,0]
	v_pk_mul_f32 v[214:215], v[214:215], s[80:81] op_sel_hi:[1,0]
	v_pk_mul_f32 v[206:207], v[206:207], v[208:209]
	v_pk_mul_f32 v[208:209], v[158:159], v[158:159]
	v_pk_mul_f32 v[206:207], v[210:211], v[206:207]
	v_pk_mul_f32 v[208:209], v[208:209], s[80:81] op_sel_hi:[1,0]
	v_pk_mul_f32 v[210:211], v[156:157], v[206:207]
	v_pk_fma_f32 v[206:207], v[156:157], v[206:207], v[156:157] neg_lo:[1,0,0] neg_hi:[1,0,0]
	v_exp_f32_e32 v208, v208
	v_cndmask_b32_e32 v206, v206, v210, vcc
	v_cmp_gt_f32_e32 vcc, 0, v157
	v_and_b32_e32 v210, 0x7fffffff, v158
	v_exp_f32_e32 v209, v209
	v_cndmask_b32_e32 v207, v207, v211, vcc
	v_and_b32_e32 v211, 0x7fffffff, v159
	v_pk_fma_f32 v[210:211], v[210:211], s[68:69], 1.0 op_sel_hi:[1,0,0]
	v_cmp_gt_f32_e32 vcc, 0, v158
	v_rcp_f32_e32 v210, v210
	v_rcp_f32_e32 v211, v211
	v_exp_f32_e32 v214, v214
	v_exp_f32_e32 v215, v215
	v_pk_mul_f32 v[218:219], v[148:149], v[148:149]
	v_pk_fma_f32 v[212:213], v[210:211], s[70:71], v[200:201] op_sel_hi:[1,0,0]
	v_pk_mul_f32 v[218:219], v[218:219], s[80:81] op_sel_hi:[1,0]
	v_pk_fma_f32 v[212:213], v[210:211], v[212:213], s[74:75] op_sel_hi:[1,1,0]
	v_exp_f32_e32 v218, v218
	v_pk_fma_f32 v[212:213], v[210:211], v[212:213], s[76:77] op_sel_hi:[1,1,0]
	v_exp_f32_e32 v219, v219
	v_pk_fma_f32 v[212:213], v[210:211], v[212:213], s[78:79] op_sel_hi:[1,1,0]
	v_pk_mul_f32 v[240:241], v[144:145], v[144:145]
	v_pk_mul_f32 v[210:211], v[210:211], v[212:213]
	v_pk_mul_f32 v[240:241], v[240:241], s[80:81] op_sel_hi:[1,0]
	v_pk_mul_f32 v[208:209], v[208:209], v[210:211]
	v_exp_f32_e32 v240, v240
	v_pk_mul_f32 v[210:211], v[158:159], v[208:209]
	v_pk_fma_f32 v[208:209], v[158:159], v[208:209], v[158:159] neg_lo:[1,0,0] neg_hi:[1,0,0]
	v_exp_f32_e32 v241, v241
	v_cndmask_b32_e32 v208, v208, v210, vcc
	v_cmp_gt_f32_e32 vcc, 0, v159
	v_and_b32_e32 v210, 0x7fffffff, v152
	v_add_f32_e32 v184, 0, v206
	v_cndmask_b32_e32 v209, v209, v211, vcc
	v_and_b32_e32 v211, 0x7fffffff, v153
	v_pk_fma_f32 v[210:211], v[210:211], s[68:69], 1.0 op_sel_hi:[1,0,0]
	v_cmp_gt_f32_e32 vcc, 0, v152
	v_rcp_f32_e32 v210, v210
	v_rcp_f32_e32 v211, v211
	v_add_f32_e32 v184, v207, v184
	v_add_f32_e32 v184, v208, v184
	v_add_f32_e32 v184, v209, v184
	v_pk_fma_f32 v[212:213], v[210:211], s[70:71], v[200:201] op_sel_hi:[1,0,0]
	v_and_b32_e32 v203, 64, v229
	v_pk_fma_f32 v[212:213], v[210:211], v[212:213], s[74:75] op_sel_hi:[1,1,0]
	v_add_u32_e32 v203, 64, v203
	v_pk_fma_f32 v[212:213], v[210:211], v[212:213], s[76:77] op_sel_hi:[1,1,0]
	s_nop 0
	v_pk_fma_f32 v[212:213], v[210:211], v[212:213], s[78:79] op_sel_hi:[1,1,0]
	s_nop 0
	v_pk_mul_f32 v[210:211], v[210:211], v[212:213]
	v_pk_mul_f32 v[212:213], v[154:155], v[154:155]
	v_pk_mul_f32 v[210:211], v[214:215], v[210:211]
	v_pk_mul_f32 v[212:213], v[212:213], s[80:81] op_sel_hi:[1,0]
	v_pk_mul_f32 v[214:215], v[152:153], v[210:211]
	v_pk_fma_f32 v[210:211], v[152:153], v[210:211], v[152:153] neg_lo:[1,0,0] neg_hi:[1,0,0]
	v_exp_f32_e32 v212, v212
	v_cndmask_b32_e32 v210, v210, v214, vcc
	v_cmp_gt_f32_e32 vcc, 0, v153
	v_and_b32_e32 v214, 0x7fffffff, v154
	v_exp_f32_e32 v213, v213
	v_cndmask_b32_e32 v211, v211, v215, vcc
	v_and_b32_e32 v215, 0x7fffffff, v155
	v_pk_fma_f32 v[214:215], v[214:215], s[68:69], 1.0 op_sel_hi:[1,0,0]
	v_cmp_gt_f32_e32 vcc, 0, v154
	v_rcp_f32_e32 v214, v214
	v_rcp_f32_e32 v215, v215
	v_add_f32_e32 v184, v210, v184
	v_add_f32_e32 v184, v211, v184
	v_pk_fma_f32 v[216:217], v[214:215], s[70:71], v[200:201] op_sel_hi:[1,0,0]
	s_nop 0
	v_pk_fma_f32 v[216:217], v[214:215], v[216:217], s[74:75] op_sel_hi:[1,1,0]
	s_nop 0
	v_pk_fma_f32 v[216:217], v[214:215], v[216:217], s[76:77] op_sel_hi:[1,1,0]
	s_nop 0
	v_pk_fma_f32 v[216:217], v[214:215], v[216:217], s[78:79] op_sel_hi:[1,1,0]
	s_nop 0
	v_pk_mul_f32 v[214:215], v[214:215], v[216:217]
	s_nop 0
	v_pk_mul_f32 v[212:213], v[212:213], v[214:215]
	s_nop 0
	v_pk_mul_f32 v[214:215], v[154:155], v[212:213]
	v_pk_fma_f32 v[212:213], v[154:155], v[212:213], v[154:155] neg_lo:[1,0,0] neg_hi:[1,0,0]
	s_nop 0
	v_cndmask_b32_e32 v212, v212, v214, vcc
	v_cmp_gt_f32_e32 vcc, 0, v155
	v_and_b32_e32 v214, 0x7fffffff, v148
	v_add_f32_e32 v184, v212, v184
	v_cndmask_b32_e32 v213, v213, v215, vcc
	v_and_b32_e32 v215, 0x7fffffff, v149
	v_pk_fma_f32 v[214:215], v[214:215], s[68:69], 1.0 op_sel_hi:[1,0,0]
	v_cmp_gt_f32_e32 vcc, 0, v148
	v_rcp_f32_e32 v214, v214
	v_rcp_f32_e32 v215, v215
	v_add_f32_e32 v184, v213, v184
	v_pk_fma_f32 v[216:217], v[214:215], s[70:71], v[200:201] op_sel_hi:[1,0,0]
	s_nop 0
	v_pk_fma_f32 v[216:217], v[214:215], v[216:217], s[74:75] op_sel_hi:[1,1,0]
	s_nop 0
	v_pk_fma_f32 v[216:217], v[214:215], v[216:217], s[76:77] op_sel_hi:[1,1,0]
	s_nop 0
	v_pk_fma_f32 v[216:217], v[214:215], v[216:217], s[78:79] op_sel_hi:[1,1,0]
	s_nop 0
	v_pk_mul_f32 v[214:215], v[214:215], v[216:217]
	v_pk_mul_f32 v[216:217], v[150:151], v[150:151]
	v_pk_mul_f32 v[214:215], v[218:219], v[214:215]
	v_pk_mul_f32 v[216:217], v[216:217], s[80:81] op_sel_hi:[1,0]
	v_pk_mul_f32 v[218:219], v[148:149], v[214:215]
	v_pk_fma_f32 v[214:215], v[148:149], v[214:215], v[148:149] neg_lo:[1,0,0] neg_hi:[1,0,0]
	v_exp_f32_e32 v216, v216
	v_cndmask_b32_e32 v214, v214, v218, vcc
	v_cmp_gt_f32_e32 vcc, 0, v149
	v_and_b32_e32 v218, 0x7fffffff, v150
	v_exp_f32_e32 v217, v217
	v_cndmask_b32_e32 v215, v215, v219, vcc
	v_and_b32_e32 v219, 0x7fffffff, v151
	v_pk_fma_f32 v[218:219], v[218:219], s[68:69], 1.0 op_sel_hi:[1,0,0]
	v_cmp_gt_f32_e32 vcc, 0, v150
	v_rcp_f32_e32 v218, v218
	v_rcp_f32_e32 v219, v219
	v_add_f32_e32 v184, v214, v184
	v_add_f32_e32 v184, v215, v184
	v_pk_fma_f32 v[220:221], v[218:219], s[70:71], v[200:201] op_sel_hi:[1,0,0]
	s_nop 0
	v_pk_fma_f32 v[220:221], v[218:219], v[220:221], s[74:75] op_sel_hi:[1,1,0]
	s_nop 0
	v_pk_fma_f32 v[220:221], v[218:219], v[220:221], s[76:77] op_sel_hi:[1,1,0]
	s_nop 0
	v_pk_fma_f32 v[220:221], v[218:219], v[220:221], s[78:79] op_sel_hi:[1,1,0]
	s_nop 0
	v_pk_mul_f32 v[218:219], v[218:219], v[220:221]
	s_nop 0
	v_pk_mul_f32 v[216:217], v[216:217], v[218:219]
	s_nop 0
	v_pk_mul_f32 v[218:219], v[150:151], v[216:217]
	v_pk_fma_f32 v[216:217], v[150:151], v[216:217], v[150:151] neg_lo:[1,0,0] neg_hi:[1,0,0]
	s_nop 0
	v_cndmask_b32_e32 v216, v216, v218, vcc
	v_cmp_gt_f32_e32 vcc, 0, v151
	v_and_b32_e32 v218, 0x7fffffff, v144
	v_add_f32_e32 v184, v216, v184
	v_cndmask_b32_e32 v217, v217, v219, vcc
	v_and_b32_e32 v219, 0x7fffffff, v145
	v_pk_fma_f32 v[218:219], v[218:219], s[68:69], 1.0 op_sel_hi:[1,0,0]
	v_cmp_gt_f32_e32 vcc, 0, v144
	v_rcp_f32_e32 v218, v218
	v_rcp_f32_e32 v219, v219
	v_add_f32_e32 v184, v217, v184
	v_pk_fma_f32 v[220:221], v[218:219], s[70:71], v[200:201] op_sel_hi:[1,0,0]
	s_nop 0
	v_pk_fma_f32 v[220:221], v[218:219], v[220:221], s[74:75] op_sel_hi:[1,1,0]
	s_nop 0
	v_pk_fma_f32 v[220:221], v[218:219], v[220:221], s[76:77] op_sel_hi:[1,1,0]
	s_nop 0
	v_pk_fma_f32 v[220:221], v[218:219], v[220:221], s[78:79] op_sel_hi:[1,1,0]
	s_nop 0
	v_pk_mul_f32 v[218:219], v[218:219], v[220:221]
	v_pk_mul_f32 v[220:221], v[146:147], v[146:147]
	v_pk_mul_f32 v[218:219], v[240:241], v[218:219]
	v_pk_mul_f32 v[220:221], v[220:221], s[80:81] op_sel_hi:[1,0]
	v_pk_mul_f32 v[240:241], v[144:145], v[218:219]
	v_pk_fma_f32 v[218:219], v[144:145], v[218:219], v[144:145] neg_lo:[1,0,0] neg_hi:[1,0,0]
	v_exp_f32_e32 v220, v220
	v_cndmask_b32_e32 v218, v218, v240, vcc
	v_cmp_gt_f32_e32 vcc, 0, v145
	v_and_b32_e32 v240, 0x7fffffff, v146
	v_exp_f32_e32 v221, v221
	v_cndmask_b32_e32 v219, v219, v241, vcc
	v_and_b32_e32 v241, 0x7fffffff, v147
	v_pk_fma_f32 v[240:241], v[240:241], s[68:69], 1.0 op_sel_hi:[1,0,0]
	v_cmp_gt_f32_e32 vcc, 0, v146
	v_rcp_f32_e32 v240, v240
	v_rcp_f32_e32 v241, v241
	v_add_f32_e32 v184, v218, v184
	v_add_f32_e32 v184, v219, v184
	v_pk_fma_f32 v[200:201], v[240:241], s[70:71], v[200:201] op_sel_hi:[1,0,0]
	s_nop 0
	v_pk_fma_f32 v[200:201], v[240:241], v[200:201], s[74:75] op_sel_hi:[1,1,0]
	s_nop 0
	v_pk_fma_f32 v[200:201], v[240:241], v[200:201], s[76:77] op_sel_hi:[1,1,0]
	s_nop 0
	v_pk_fma_f32 v[200:201], v[240:241], v[200:201], s[78:79] op_sel_hi:[1,1,0]
	s_nop 0
	v_pk_mul_f32 v[200:201], v[240:241], v[200:201]
	s_nop 0
	v_pk_mul_f32 v[200:201], v[220:221], v[200:201]
	s_nop 0
	v_pk_mul_f32 v[220:221], v[146:147], v[200:201]
	v_pk_fma_f32 v[200:201], v[146:147], v[200:201], v[146:147] neg_lo:[1,0,0] neg_hi:[1,0,0]
	s_nop 0
	v_cndmask_b32_e32 v220, v200, v220, vcc
	v_cmp_gt_f32_e32 vcc, 0, v147
	v_xor_b32_e32 v200, 16, v229
	v_add_f32_e32 v184, v220, v184
	v_cndmask_b32_e32 v221, v201, v221, vcc
	v_mul_f32_e32 v201, v207, v207
	v_fmac_f32_e32 v201, v206, v206
	v_fmac_f32_e32 v201, v208, v208
	v_fmac_f32_e32 v201, v209, v209
	v_fmac_f32_e32 v201, v210, v210
	v_fmac_f32_e32 v201, v211, v211
	v_fmac_f32_e32 v201, v212, v212
	v_fmac_f32_e32 v201, v213, v213
	v_fmac_f32_e32 v201, v214, v214
	v_fmac_f32_e32 v201, v215, v215
	v_fmac_f32_e32 v201, v216, v216
	v_cmp_lt_i32_e32 vcc, v200, v203
	v_fmac_f32_e32 v201, v217, v217
	v_fmac_f32_e32 v201, v218, v218
	v_cndmask_b32_e32 v200, v229, v200, vcc
	v_add_f32_e32 v184, v221, v184
	v_lshlrev_b32_e32 v205, 2, v200
	v_fmac_f32_e32 v201, v219, v219
	v_mov_b32_e32 v200, v184
	s_nop 1
	v_permlane16_swap_b32_e32 v184, v200
	s_nop 1
	v_fmac_f32_e32 v201, v220, v220
	v_fmac_f32_e32 v201, v221, v221
	v_mov_b32_e32 v205, v201
	s_nop 1
	v_permlane16_swap_b32_e32 v201, v205
	s_nop 1
	s_waitcnt lgkmcnt(1)
	v_add_f32_e32 v184, v184, v200
	v_xor_b32_e32 v200, 32, v229
	v_cmp_lt_i32_e32 vcc, v200, v203
	s_waitcnt lgkmcnt(0)
	v_add_f32_e32 v201, v201, v205
	v_cndmask_b32_e32 v200, v229, v200, vcc
	v_lshlrev_b32_e32 v203, 2, v200
	v_mov_b32_e32 v200, v184
	s_nop 1
	v_permlane32_swap_b32_e32 v184, v200
	s_nop 1
	v_mov_b32_e32 v203, v201
	s_nop 1
	v_permlane32_swap_b32_e32 v201, v203
	s_nop 1
	s_and_saveexec_b64 s[94:95], s[4:5]
	s_cbranch_execz .LBB0_571
	v_lshlrev_b64 v[240:241], 2, v[198:199]
	v_lshl_add_u64 v[242:243], s[14:15], 0, v[240:241]
	v_lshl_add_u64 v[240:241], s[52:53], 0, v[240:241]
	s_waitcnt lgkmcnt(1)
	v_add_f32_e32 v184, v184, v200
	s_waitcnt lgkmcnt(0)
	v_add_f32_e32 v200, v201, v203
	global_atomic_add_f32 v[240:241], v184, off
	global_atomic_add_f32 v[242:243], v200, off

.LBB0_575:
	s_add_u32 s0, s28, s12
	s_addc_u32 s10, s29, s13
	s_cmp_eq_u32 s83, 3
	s_cselect_b32 s11, s27, s10
	s_cselect_b32 s10, s26, s0
	v_lshlrev_b32_e32 v184, 1, v202
	s_waitcnt lgkmcnt(0)
	v_lshl_add_u64 v[202:203], s[10:11], 0, v[184:185]
	v_lshlrev_b64 v[146:147], 11, v[198:199]
	v_lshl_add_u64 v[150:151], v[202:203], 0, v[146:147]
	v_cvt_pk_bf16_f32 v146, v206, v207
	v_cvt_pk_bf16_f32 v147, v208, v209
	v_cvt_pk_bf16_f32 v148, v210, v211
	v_cvt_pk_bf16_f32 v149, v212, v213
	global_store_dwordx4 v[150:151], v[146:149], off
	v_or_b32_e32 v144, 16, v198
	v_ashrrev_i32_e32 v145, 31, v144
	v_fmamk_f32 v148, v231, 0x3a800000, v228
	v_rsq_f32_e32 v152, v148
	v_cvt_pk_bf16_f32 v146, v214, v215
	v_cvt_pk_bf16_f32 v147, v216, v217
	v_cvt_pk_bf16_f32 v148, v218, v219
	v_cvt_pk_bf16_f32 v149, v220, v221
	global_store_dwordx4 v[150:151], v[146:149], off offset:256
	v_pk_fma_f32 v[110:111], v[110:111], v[152:153], v[46:47] op_sel_hi:[1,0,1]
	v_pk_fma_f32 v[108:109], v[108:109], v[152:153], v[44:45] op_sel_hi:[1,0,1]
	v_cndmask_b32_e64 v146, 0, 1, s[92:93]
	v_pk_fma_f32 v[106:107], v[106:107], v[152:153], v[42:43] op_sel_hi:[1,0,1]
	v_pk_fma_f32 v[104:105], v[104:105], v[152:153], v[40:41] op_sel_hi:[1,0,1]
	v_pk_fma_f32 v[102:103], v[102:103], v[152:153], v[38:39] op_sel_hi:[1,0,1]
	v_pk_fma_f32 v[100:101], v[100:101], v[152:153], v[36:37] op_sel_hi:[1,0,1]
	v_pk_fma_f32 v[98:99], v[98:99], v[152:153], v[34:35] op_sel_hi:[1,0,1]
	v_pk_fma_f32 v[96:97], v[96:97], v[152:153], v[32:33] op_sel_hi:[1,0,1]
	v_cmp_ne_u32_e64 s[10:11], 1, v146
	s_andn2_b64 vcc, exec, s[92:93]
	s_mov_b64 s[12:13], -1
	s_cbranch_vccnz .LBB0_581
	s_and_b64 vcc, exec, s[8:9]
	v_mov_b32_e32 v149, v111
	v_mov_b32_e32 v148, v110
	v_mov_b32_e32 v147, v109
	v_mov_b32_e32 v146, v108
	v_mov_b32_e32 v153, v107
	v_mov_b32_e32 v152, v106
	v_mov_b32_e32 v151, v105
	v_mov_b32_e32 v150, v104
	v_mov_b32_e32 v157, v103
	v_mov_b32_e32 v156, v102
	v_mov_b32_e32 v155, v101
	v_mov_b32_e32 v154, v100
	v_mov_b32_e32 v207, v99
	v_mov_b32_e32 v206, v98
	v_mov_b32_e32 v159, v97
	v_mov_b32_e32 v158, v96
	s_cbranch_vccnz .LBB0_580
	v_and_b32_e32 v147, 0x7fffffff, v109
	v_and_b32_e32 v146, 0x7fffffff, v108
	v_pk_fma_f32 v[146:147], v[146:147], s[68:69], 1.0 op_sel_hi:[1,0,0]
	v_mov_b64_e32 v[206:207], s[72:73]
	v_rcp_f32_e32 v146, v146
	v_rcp_f32_e32 v147, v147
	v_pk_mul_f32 v[150:151], v[108:109], v[108:109]
	v_and_b32_e32 v153, 0x7fffffff, v111
	v_pk_mul_f32 v[150:151], v[150:151], s[80:81] op_sel_hi:[1,0]
	v_pk_fma_f32 v[148:149], v[146:147], s[70:71], v[206:207] op_sel_hi:[1,0,0]
	v_exp_f32_e32 v150, v150
	v_pk_fma_f32 v[148:149], v[146:147], v[148:149], s[74:75] op_sel_hi:[1,1,0]
	v_exp_f32_e32 v151, v151
	v_pk_fma_f32 v[148:149], v[146:147], v[148:149], s[76:77] op_sel_hi:[1,1,0]
	v_and_b32_e32 v152, 0x7fffffff, v110
	v_pk_fma_f32 v[148:149], v[146:147], v[148:149], s[78:79] op_sel_hi:[1,1,0]
	v_pk_fma_f32 v[152:153], v[152:153], s[68:69], 1.0 op_sel_hi:[1,0,0]
	v_pk_mul_f32 v[146:147], v[146:147], v[148:149]
	v_rcp_f32_e32 v152, v152
	v_rcp_f32_e32 v153, v153
	v_pk_mul_f32 v[146:147], v[150:151], v[146:147]
	v_cmp_gt_f32_e32 vcc, 0, v108
	v_pk_mul_f32 v[150:151], v[108:109], v[146:147]
	v_pk_fma_f32 v[146:147], v[108:109], v[146:147], v[108:109] neg_lo:[1,0,0] neg_hi:[1,0,0]
	v_pk_mul_f32 v[148:149], v[110:111], v[110:111]
	v_cndmask_b32_e32 v146, v146, v150, vcc
	v_cmp_gt_f32_e32 vcc, 0, v109
	v_pk_mul_f32 v[148:149], v[148:149], s[80:81] op_sel_hi:[1,0]
	v_pk_mul_f32 v[154:155], v[104:105], v[104:105]
	v_cndmask_b32_e32 v147, v147, v151, vcc
	v_pk_fma_f32 v[150:151], v[152:153], s[70:71], v[206:207] op_sel_hi:[1,0,0]
	v_exp_f32_e32 v148, v148
	v_pk_fma_f32 v[150:151], v[152:153], v[150:151], s[74:75] op_sel_hi:[1,1,0]
	v_exp_f32_e32 v149, v149
	v_pk_fma_f32 v[150:151], v[152:153], v[150:151], s[76:77] op_sel_hi:[1,1,0]
	v_cmp_gt_f32_e32 vcc, 0, v110
	v_pk_fma_f32 v[150:151], v[152:153], v[150:151], s[78:79] op_sel_hi:[1,1,0]
	v_pk_mul_f32 v[154:155], v[154:155], s[80:81] op_sel_hi:[1,0]
	v_pk_mul_f32 v[150:151], v[152:153], v[150:151]
	v_and_b32_e32 v153, 0x7fffffff, v105
	v_and_b32_e32 v152, 0x7fffffff, v104
	v_pk_fma_f32 v[152:153], v[152:153], s[68:69], 1.0 op_sel_hi:[1,0,0]
	v_pk_mul_f32 v[148:149], v[148:149], v[150:151]
	v_rcp_f32_e32 v152, v152
	v_rcp_f32_e32 v153, v153
	v_pk_mul_f32 v[150:151], v[110:111], v[148:149]
	v_pk_fma_f32 v[148:149], v[110:111], v[148:149], v[110:111] neg_lo:[1,0,0] neg_hi:[1,0,0]
	v_exp_f32_e32 v154, v154
	v_cndmask_b32_e32 v148, v148, v150, vcc
	v_cmp_gt_f32_e32 vcc, 0, v111
	v_exp_f32_e32 v155, v155
	v_and_b32_e32 v157, 0x7fffffff, v107
	v_cndmask_b32_e32 v149, v149, v151, vcc
	v_pk_fma_f32 v[150:151], v[152:153], s[70:71], v[206:207] op_sel_hi:[1,0,0]
	v_and_b32_e32 v156, 0x7fffffff, v106
	v_pk_fma_f32 v[150:151], v[152:153], v[150:151], s[74:75] op_sel_hi:[1,1,0]
	v_pk_fma_f32 v[156:157], v[156:157], s[68:69], 1.0 op_sel_hi:[1,0,0]
	v_pk_fma_f32 v[150:151], v[152:153], v[150:151], s[76:77] op_sel_hi:[1,1,0]
	v_rcp_f32_e32 v156, v156
	v_pk_fma_f32 v[150:151], v[152:153], v[150:151], s[78:79] op_sel_hi:[1,1,0]
	v_rcp_f32_e32 v157, v157
	v_pk_mul_f32 v[150:151], v[152:153], v[150:151]
	v_cmp_gt_f32_e32 vcc, 0, v104
	v_pk_mul_f32 v[150:151], v[154:155], v[150:151]
	v_pk_mul_f32 v[152:153], v[106:107], v[106:107]
	v_pk_mul_f32 v[154:155], v[104:105], v[150:151]
	v_pk_fma_f32 v[150:151], v[104:105], v[150:151], v[104:105] neg_lo:[1,0,0] neg_hi:[1,0,0]
	v_pk_mul_f32 v[152:153], v[152:153], s[80:81] op_sel_hi:[1,0]
	v_cndmask_b32_e32 v150, v150, v154, vcc
	v_cmp_gt_f32_e32 vcc, 0, v105
	v_exp_f32_e32 v152, v152
	v_exp_f32_e32 v153, v153
	v_cndmask_b32_e32 v151, v151, v155, vcc
	v_pk_fma_f32 v[154:155], v[156:157], s[70:71], v[206:207] op_sel_hi:[1,0,0]
	v_cmp_gt_f32_e32 vcc, 0, v106
	v_pk_fma_f32 v[154:155], v[156:157], v[154:155], s[74:75] op_sel_hi:[1,1,0]
	v_pk_mul_f32 v[158:159], v[100:101], v[100:101]
	v_pk_fma_f32 v[154:155], v[156:157], v[154:155], s[76:77] op_sel_hi:[1,1,0]
	v_pk_mul_f32 v[158:159], v[158:159], s[80:81] op_sel_hi:[1,0]
	v_pk_fma_f32 v[154:155], v[156:157], v[154:155], s[78:79] op_sel_hi:[1,1,0]
	v_exp_f32_e32 v158, v158
	v_pk_mul_f32 v[154:155], v[156:157], v[154:155]
	v_and_b32_e32 v157, 0x7fffffff, v101
	v_and_b32_e32 v156, 0x7fffffff, v100
	v_pk_fma_f32 v[156:157], v[156:157], s[68:69], 1.0 op_sel_hi:[1,0,0]
	v_pk_mul_f32 v[152:153], v[152:153], v[154:155]
	v_rcp_f32_e32 v156, v156
	v_rcp_f32_e32 v157, v157
	v_pk_mul_f32 v[154:155], v[106:107], v[152:153]
	v_pk_fma_f32 v[152:153], v[106:107], v[152:153], v[106:107] neg_lo:[1,0,0] neg_hi:[1,0,0]
	v_exp_f32_e32 v159, v159
	v_cndmask_b32_e32 v152, v152, v154, vcc
	v_cmp_gt_f32_e32 vcc, 0, v107
	v_and_b32_e32 v209, 0x7fffffff, v103
	v_and_b32_e32 v208, 0x7fffffff, v102
	v_cndmask_b32_e32 v153, v153, v155, vcc
	v_pk_fma_f32 v[154:155], v[156:157], s[70:71], v[206:207] op_sel_hi:[1,0,0]
	v_pk_fma_f32 v[208:209], v[208:209], s[68:69], 1.0 op_sel_hi:[1,0,0]
	v_pk_fma_f32 v[154:155], v[156:157], v[154:155], s[74:75] op_sel_hi:[1,1,0]
	v_rcp_f32_e32 v208, v208
	v_pk_fma_f32 v[154:155], v[156:157], v[154:155], s[76:77] op_sel_hi:[1,1,0]
	v_rcp_f32_e32 v209, v209
	v_pk_fma_f32 v[154:155], v[156:157], v[154:155], s[78:79] op_sel_hi:[1,1,0]
	v_cmp_gt_f32_e32 vcc, 0, v100
	v_pk_mul_f32 v[154:155], v[156:157], v[154:155]
	v_pk_mul_f32 v[156:157], v[102:103], v[102:103]
	v_pk_mul_f32 v[154:155], v[158:159], v[154:155]
	v_pk_mul_f32 v[156:157], v[156:157], s[80:81] op_sel_hi:[1,0]
	v_pk_mul_f32 v[158:159], v[100:101], v[154:155]
	v_pk_fma_f32 v[154:155], v[100:101], v[154:155], v[100:101] neg_lo:[1,0,0] neg_hi:[1,0,0]
	v_exp_f32_e32 v156, v156
	v_cndmask_b32_e32 v154, v154, v158, vcc
	v_cmp_gt_f32_e32 vcc, 0, v101
	v_exp_f32_e32 v157, v157
	v_and_b32_e32 v213, 0x7fffffff, v99
	v_cndmask_b32_e32 v155, v155, v159, vcc
	v_pk_fma_f32 v[158:159], v[208:209], s[70:71], v[206:207] op_sel_hi:[1,0,0]
	v_cmp_gt_f32_e32 vcc, 0, v102
	v_pk_fma_f32 v[158:159], v[208:209], v[158:159], s[74:75] op_sel_hi:[1,1,0]
	v_and_b32_e32 v212, 0x7fffffff, v98
	v_pk_fma_f32 v[158:159], v[208:209], v[158:159], s[76:77] op_sel_hi:[1,1,0]
	v_pk_fma_f32 v[212:213], v[212:213], s[68:69], 1.0 op_sel_hi:[1,0,0]
	v_pk_fma_f32 v[158:159], v[208:209], v[158:159], s[78:79] op_sel_hi:[1,1,0]
	v_rcp_f32_e32 v212, v212
	v_pk_mul_f32 v[158:159], v[208:209], v[158:159]
	v_and_b32_e32 v209, 0x7fffffff, v97
	v_and_b32_e32 v208, 0x7fffffff, v96
	v_pk_fma_f32 v[208:209], v[208:209], s[68:69], 1.0 op_sel_hi:[1,0,0]
	v_pk_mul_f32 v[156:157], v[156:157], v[158:159]
	v_rcp_f32_e32 v208, v208
	v_rcp_f32_e32 v209, v209
	v_pk_mul_f32 v[158:159], v[102:103], v[156:157]
	v_pk_fma_f32 v[156:157], v[102:103], v[156:157], v[102:103] neg_lo:[1,0,0] neg_hi:[1,0,0]
	v_rcp_f32_e32 v213, v213
	v_cndmask_b32_e32 v156, v156, v158, vcc
	v_cmp_gt_f32_e32 vcc, 0, v103
	v_add_f32_e32 v184, 0, v146
	v_pk_mul_f32 v[210:211], v[96:97], v[96:97]
	v_cndmask_b32_e32 v157, v157, v159, vcc
	v_pk_fma_f32 v[158:159], v[208:209], s[70:71], v[206:207] op_sel_hi:[1,0,0]
	v_add_f32_e32 v184, v147, v184
	v_pk_fma_f32 v[158:159], v[208:209], v[158:159], s[74:75] op_sel_hi:[1,1,0]
	v_pk_mul_f32 v[210:211], v[210:211], s[80:81] op_sel_hi:[1,0]
	v_pk_fma_f32 v[158:159], v[208:209], v[158:159], s[76:77] op_sel_hi:[1,1,0]
	v_add_f32_e32 v184, v148, v184
	v_pk_fma_f32 v[158:159], v[208:209], v[158:159], s[78:79] op_sel_hi:[1,1,0]
	v_exp_f32_e32 v210, v210
	v_exp_f32_e32 v211, v211
	v_pk_mul_f32 v[158:159], v[208:209], v[158:159]
	v_pk_mul_f32 v[208:209], v[98:99], v[98:99]
	v_mul_f32_e32 v205, v147, v147
	v_add_f32_e32 v184, v149, v184
	v_pk_fma_f32 v[206:207], v[212:213], s[70:71], v[206:207] op_sel_hi:[1,0,0]
	v_pk_mul_f32 v[208:209], v[208:209], s[80:81] op_sel_hi:[1,0]
	v_fmac_f32_e32 v205, v146, v146
	v_add_f32_e32 v184, v150, v184
	v_pk_fma_f32 v[206:207], v[212:213], v[206:207], s[74:75] op_sel_hi:[1,1,0]
	v_exp_f32_e32 v208, v208
	v_exp_f32_e32 v209, v209
	v_fmac_f32_e32 v205, v148, v148
	v_add_f32_e32 v184, v151, v184
	v_pk_fma_f32 v[206:207], v[212:213], v[206:207], s[76:77] op_sel_hi:[1,1,0]
	v_fmac_f32_e32 v205, v149, v149
	v_add_f32_e32 v184, v152, v184
	v_pk_mul_f32 v[158:159], v[210:211], v[158:159]
	v_pk_fma_f32 v[206:207], v[212:213], v[206:207], s[78:79] op_sel_hi:[1,1,0]
	v_fmac_f32_e32 v205, v150, v150
	v_add_f32_e32 v184, v153, v184
	v_pk_mul_f32 v[210:211], v[96:97], v[158:159]
	v_pk_fma_f32 v[158:159], v[96:97], v[158:159], v[96:97] neg_lo:[1,0,0] neg_hi:[1,0,0]
	v_cmp_gt_f32_e32 vcc, 0, v96
	v_pk_mul_f32 v[206:207], v[212:213], v[206:207]
	v_fmac_f32_e32 v205, v151, v151
	v_add_f32_e32 v184, v154, v184
	v_cndmask_b32_e32 v158, v158, v210, vcc
	v_cmp_gt_f32_e32 vcc, 0, v97
	v_pk_mul_f32 v[206:207], v[208:209], v[206:207]
	v_fmac_f32_e32 v205, v152, v152
	v_add_f32_e32 v184, v155, v184
	v_cndmask_b32_e32 v159, v159, v211, vcc
	v_pk_mul_f32 v[208:209], v[98:99], v[206:207]
	v_pk_fma_f32 v[206:207], v[98:99], v[206:207], v[98:99] neg_lo:[1,0,0] neg_hi:[1,0,0]
	v_cmp_gt_f32_e32 vcc, 0, v98
	v_fmac_f32_e32 v205, v153, v153
	v_add_f32_e32 v184, v156, v184
	v_cndmask_b32_e32 v206, v206, v208, vcc
	v_fmac_f32_e32 v205, v154, v154
	v_add_f32_e32 v184, v157, v184
	v_and_b32_e32 v208, 64, v229
	v_cmp_gt_f32_e32 vcc, 0, v99
	v_fmac_f32_e32 v205, v155, v155
	v_add_f32_e32 v184, v158, v184
	v_xor_b32_e32 v199, 16, v229
	v_add_u32_e32 v208, 64, v208
	v_cndmask_b32_e32 v207, v207, v209, vcc
	v_fmac_f32_e32 v205, v156, v156
	v_add_f32_e32 v184, v159, v184
	v_cmp_lt_i32_e32 vcc, v199, v208
	v_fmac_f32_e32 v205, v157, v157
	v_add_f32_e32 v184, v206, v184
	v_cndmask_b32_e32 v199, v229, v199, vcc
	v_add_f32_e32 v184, v207, v184
	v_lshlrev_b32_e32 v199, 2, v199
	v_fmac_f32_e32 v205, v158, v158
	v_mov_b32_e32 v209, v184
	s_nop 1
	v_permlane16_swap_b32_e32 v184, v209
	s_nop 1
	v_fmac_f32_e32 v205, v159, v159
	v_fmac_f32_e32 v205, v206, v206
	v_fmac_f32_e32 v205, v207, v207
	v_mov_b32_e32 v210, v205
	s_nop 1
	v_permlane16_swap_b32_e32 v205, v210
	s_nop 1
	s_waitcnt lgkmcnt(1)
	v_add_f32_e32 v184, v184, v209
	v_xor_b32_e32 v209, 32, v229
	v_cmp_lt_i32_e32 vcc, v209, v208
	s_waitcnt lgkmcnt(0)
	v_add_f32_e32 v205, v205, v210
	v_cndmask_b32_e32 v199, v229, v209, vcc
	v_lshlrev_b32_e32 v208, 2, v199
	v_mov_b32_e32 v199, v184
	s_nop 1
	v_permlane32_swap_b32_e32 v184, v199
	s_nop 1
	v_mov_b32_e32 v208, v205
	s_nop 1
	v_permlane32_swap_b32_e32 v205, v208
	s_nop 1
	s_and_saveexec_b64 s[12:13], s[4:5]
	s_cbranch_execz .LBB0_579
	v_lshlrev_b64 v[210:211], 2, v[144:145]
	v_lshl_add_u64 v[212:213], s[14:15], 0, v[210:211]
	v_lshl_add_u64 v[210:211], s[52:53], 0, v[210:211]
	s_waitcnt lgkmcnt(1)
	v_add_f32_e32 v184, v184, v199
	s_waitcnt lgkmcnt(0)
	v_add_f32_e32 v199, v205, v208
	global_atomic_add_f32 v[210:211], v184, off
	global_atomic_add_f32 v[212:213], v199, off

.LBB0_585:
	v_fmamk_f32 v184, v239, 0x3a800000, v228
	v_rsq_f32_e32 v184, v184
	v_or_b32_e32 v204, 32, v198
	v_ashrrev_i32_e32 v205, 31, v204
	s_and_b64 vcc, exec, s[10:11]
	v_pk_fma_f32 v[174:175], v[174:175], v[184:185], v[46:47] op_sel_hi:[1,0,1]
	v_pk_fma_f32 v[172:173], v[172:173], v[184:185], v[44:45] op_sel_hi:[1,0,1]
	v_pk_fma_f32 v[170:171], v[170:171], v[184:185], v[42:43] op_sel_hi:[1,0,1]
	v_pk_fma_f32 v[168:169], v[168:169], v[184:185], v[40:41] op_sel_hi:[1,0,1]
	v_pk_fma_f32 v[166:167], v[166:167], v[184:185], v[38:39] op_sel_hi:[1,0,1]
	v_pk_fma_f32 v[164:165], v[164:165], v[184:185], v[36:37] op_sel_hi:[1,0,1]
	v_pk_fma_f32 v[162:163], v[162:163], v[184:185], v[34:35] op_sel_hi:[1,0,1]
	v_pk_fma_f32 v[160:161], v[160:161], v[184:185], v[32:33] op_sel_hi:[1,0,1]
	s_mov_b64 s[90:91], -1
	s_cbranch_vccnz .LBB0_591
	s_and_b64 vcc, exec, s[8:9]
	v_mov_b32_e32 v209, v175
	s_waitcnt lgkmcnt(0)
	v_mov_b32_e32 v208, v174
	v_mov_b32_e32 v207, v173
	v_mov_b32_e32 v206, v172
	v_mov_b32_e32 v213, v171
	v_mov_b32_e32 v212, v170
	v_mov_b32_e32 v211, v169
	v_mov_b32_e32 v210, v168
	v_mov_b32_e32 v217, v167
	v_mov_b32_e32 v216, v166
	v_mov_b32_e32 v215, v165
	v_mov_b32_e32 v214, v164
	v_mov_b32_e32 v221, v163
	v_mov_b32_e32 v220, v162
	v_mov_b32_e32 v219, v161
	v_mov_b32_e32 v218, v160
	s_cbranch_vccnz .LBB0_590
	v_and_b32_e32 v207, 0x7fffffff, v173
	v_and_b32_e32 v206, 0x7fffffff, v172
	v_pk_fma_f32 v[206:207], v[206:207], s[68:69], 1.0 op_sel_hi:[1,0,0]
	v_mov_b64_e32 v[220:221], s[72:73]
	v_rcp_f32_e32 v206, v206
	v_rcp_f32_e32 v207, v207
	v_pk_mul_f32 v[210:211], v[172:173], v[172:173]
	v_and_b32_e32 v213, 0x7fffffff, v175
	v_pk_mul_f32 v[210:211], v[210:211], s[80:81] op_sel_hi:[1,0]
	v_pk_fma_f32 v[208:209], v[206:207], s[70:71], v[220:221] op_sel_hi:[1,0,0]
	v_exp_f32_e32 v210, v210
	v_pk_fma_f32 v[208:209], v[206:207], v[208:209], s[74:75] op_sel_hi:[1,1,0]
	v_exp_f32_e32 v211, v211
	v_pk_fma_f32 v[208:209], v[206:207], v[208:209], s[76:77] op_sel_hi:[1,1,0]
	v_and_b32_e32 v212, 0x7fffffff, v174
	v_pk_fma_f32 v[208:209], v[206:207], v[208:209], s[78:79] op_sel_hi:[1,1,0]
	v_pk_fma_f32 v[212:213], v[212:213], s[68:69], 1.0 op_sel_hi:[1,0,0]
	v_pk_mul_f32 v[206:207], v[206:207], v[208:209]
	v_rcp_f32_e32 v212, v212
	v_rcp_f32_e32 v213, v213
	v_pk_mul_f32 v[206:207], v[210:211], v[206:207]
	v_cmp_gt_f32_e32 vcc, 0, v172
	v_pk_mul_f32 v[210:211], v[172:173], v[206:207]
	v_pk_fma_f32 v[206:207], v[172:173], v[206:207], v[172:173] neg_lo:[1,0,0] neg_hi:[1,0,0]
	v_pk_mul_f32 v[208:209], v[174:175], v[174:175]
	v_cndmask_b32_e32 v206, v206, v210, vcc
	v_cmp_gt_f32_e32 vcc, 0, v173
	v_pk_mul_f32 v[208:209], v[208:209], s[80:81] op_sel_hi:[1,0]
	v_pk_mul_f32 v[214:215], v[168:169], v[168:169]
	v_cndmask_b32_e32 v207, v207, v211, vcc
	v_pk_fma_f32 v[210:211], v[212:213], s[70:71], v[220:221] op_sel_hi:[1,0,0]
	v_exp_f32_e32 v208, v208
	v_pk_fma_f32 v[210:211], v[212:213], v[210:211], s[74:75] op_sel_hi:[1,1,0]
	v_exp_f32_e32 v209, v209
	v_pk_fma_f32 v[210:211], v[212:213], v[210:211], s[76:77] op_sel_hi:[1,1,0]
	v_cmp_gt_f32_e32 vcc, 0, v174
	v_pk_fma_f32 v[210:211], v[212:213], v[210:211], s[78:79] op_sel_hi:[1,1,0]
	v_pk_mul_f32 v[214:215], v[214:215], s[80:81] op_sel_hi:[1,0]
	v_pk_mul_f32 v[210:211], v[212:213], v[210:211]
	v_and_b32_e32 v213, 0x7fffffff, v169
	v_and_b32_e32 v212, 0x7fffffff, v168
	v_pk_fma_f32 v[212:213], v[212:213], s[68:69], 1.0 op_sel_hi:[1,0,0]
	v_pk_mul_f32 v[208:209], v[208:209], v[210:211]
	v_rcp_f32_e32 v212, v212
	v_rcp_f32_e32 v213, v213
	v_pk_mul_f32 v[210:211], v[174:175], v[208:209]
	v_pk_fma_f32 v[208:209], v[174:175], v[208:209], v[174:175] neg_lo:[1,0,0] neg_hi:[1,0,0]
	v_exp_f32_e32 v214, v214
	v_cndmask_b32_e32 v208, v208, v210, vcc
	v_cmp_gt_f32_e32 vcc, 0, v175
	v_exp_f32_e32 v215, v215
	v_and_b32_e32 v217, 0x7fffffff, v171
	v_cndmask_b32_e32 v209, v209, v211, vcc
	v_pk_fma_f32 v[210:211], v[212:213], s[70:71], v[220:221] op_sel_hi:[1,0,0]
	v_and_b32_e32 v216, 0x7fffffff, v170
	v_pk_fma_f32 v[210:211], v[212:213], v[210:211], s[74:75] op_sel_hi:[1,1,0]
	v_pk_fma_f32 v[216:217], v[216:217], s[68:69], 1.0 op_sel_hi:[1,0,0]
	v_pk_fma_f32 v[210:211], v[212:213], v[210:211], s[76:77] op_sel_hi:[1,1,0]
	v_rcp_f32_e32 v216, v216
	v_pk_fma_f32 v[210:211], v[212:213], v[210:211], s[78:79] op_sel_hi:[1,1,0]
	v_rcp_f32_e32 v217, v217
	v_pk_mul_f32 v[210:211], v[212:213], v[210:211]
	v_cmp_gt_f32_e32 vcc, 0, v168
	v_pk_mul_f32 v[210:211], v[214:215], v[210:211]
	v_pk_mul_f32 v[212:213], v[170:171], v[170:171]
	v_pk_mul_f32 v[214:215], v[168:169], v[210:211]
	v_pk_fma_f32 v[210:211], v[168:169], v[210:211], v[168:169] neg_lo:[1,0,0] neg_hi:[1,0,0]
	v_pk_mul_f32 v[212:213], v[212:213], s[80:81] op_sel_hi:[1,0]
	v_cndmask_b32_e32 v210, v210, v214, vcc
	v_cmp_gt_f32_e32 vcc, 0, v169
	v_exp_f32_e32 v212, v212
	v_exp_f32_e32 v213, v213
	v_cndmask_b32_e32 v211, v211, v215, vcc
	v_pk_fma_f32 v[214:215], v[216:217], s[70:71], v[220:221] op_sel_hi:[1,0,0]
	v_cmp_gt_f32_e32 vcc, 0, v170
	v_pk_fma_f32 v[214:215], v[216:217], v[214:215], s[74:75] op_sel_hi:[1,1,0]
	v_pk_mul_f32 v[218:219], v[164:165], v[164:165]
	v_pk_fma_f32 v[214:215], v[216:217], v[214:215], s[76:77] op_sel_hi:[1,1,0]
	v_pk_mul_f32 v[218:219], v[218:219], s[80:81] op_sel_hi:[1,0]
	v_pk_fma_f32 v[214:215], v[216:217], v[214:215], s[78:79] op_sel_hi:[1,1,0]
	v_exp_f32_e32 v218, v218
	v_pk_mul_f32 v[214:215], v[216:217], v[214:215]
	v_and_b32_e32 v217, 0x7fffffff, v165
	v_and_b32_e32 v216, 0x7fffffff, v164
	v_pk_fma_f32 v[216:217], v[216:217], s[68:69], 1.0 op_sel_hi:[1,0,0]
	v_pk_mul_f32 v[212:213], v[212:213], v[214:215]
	v_rcp_f32_e32 v216, v216
	v_rcp_f32_e32 v217, v217
	v_pk_mul_f32 v[214:215], v[170:171], v[212:213]
	v_pk_fma_f32 v[212:213], v[170:171], v[212:213], v[170:171] neg_lo:[1,0,0] neg_hi:[1,0,0]
	v_exp_f32_e32 v219, v219
	v_cndmask_b32_e32 v212, v212, v214, vcc
	v_cmp_gt_f32_e32 vcc, 0, v171
	v_and_b32_e32 v241, 0x7fffffff, v167
	v_and_b32_e32 v240, 0x7fffffff, v166
	v_cndmask_b32_e32 v213, v213, v215, vcc
	v_pk_fma_f32 v[214:215], v[216:217], s[70:71], v[220:221] op_sel_hi:[1,0,0]
	v_pk_fma_f32 v[240:241], v[240:241], s[68:69], 1.0 op_sel_hi:[1,0,0]
	v_pk_fma_f32 v[214:215], v[216:217], v[214:215], s[74:75] op_sel_hi:[1,1,0]
	v_rcp_f32_e32 v240, v240
	v_pk_fma_f32 v[214:215], v[216:217], v[214:215], s[76:77] op_sel_hi:[1,1,0]
	v_rcp_f32_e32 v241, v241
	v_pk_fma_f32 v[214:215], v[216:217], v[214:215], s[78:79] op_sel_hi:[1,1,0]
	v_cmp_gt_f32_e32 vcc, 0, v164
	v_pk_mul_f32 v[214:215], v[216:217], v[214:215]
	v_pk_mul_f32 v[216:217], v[166:167], v[166:167]
	v_pk_mul_f32 v[214:215], v[218:219], v[214:215]
	v_pk_mul_f32 v[216:217], v[216:217], s[80:81] op_sel_hi:[1,0]
	v_pk_mul_f32 v[218:219], v[164:165], v[214:215]
	v_pk_fma_f32 v[214:215], v[164:165], v[214:215], v[164:165] neg_lo:[1,0,0] neg_hi:[1,0,0]
	v_exp_f32_e32 v216, v216
	v_cndmask_b32_e32 v214, v214, v218, vcc
	v_cmp_gt_f32_e32 vcc, 0, v165
	v_exp_f32_e32 v217, v217
	v_and_b32_e32 v245, 0x7fffffff, v163
	v_cndmask_b32_e32 v215, v215, v219, vcc
	v_pk_fma_f32 v[218:219], v[240:241], s[70:71], v[220:221] op_sel_hi:[1,0,0]
	v_cmp_gt_f32_e32 vcc, 0, v166
	v_pk_fma_f32 v[218:219], v[240:241], v[218:219], s[74:75] op_sel_hi:[1,1,0]
	v_and_b32_e32 v244, 0x7fffffff, v162
	v_pk_fma_f32 v[218:219], v[240:241], v[218:219], s[76:77] op_sel_hi:[1,1,0]
	v_pk_fma_f32 v[244:245], v[244:245], s[68:69], 1.0 op_sel_hi:[1,0,0]
	v_pk_fma_f32 v[218:219], v[240:241], v[218:219], s[78:79] op_sel_hi:[1,1,0]
	v_add_f32_e32 v184, 0, v206
	v_pk_mul_f32 v[218:219], v[240:241], v[218:219]
	v_and_b32_e32 v241, 0x7fffffff, v161
	v_and_b32_e32 v240, 0x7fffffff, v160
	v_pk_fma_f32 v[240:241], v[240:241], s[68:69], 1.0 op_sel_hi:[1,0,0]
	v_pk_mul_f32 v[216:217], v[216:217], v[218:219]
	v_rcp_f32_e32 v240, v240
	v_rcp_f32_e32 v241, v241
	v_pk_mul_f32 v[218:219], v[166:167], v[216:217]
	v_pk_fma_f32 v[216:217], v[166:167], v[216:217], v[166:167] neg_lo:[1,0,0] neg_hi:[1,0,0]
	v_rcp_f32_e32 v244, v244
	v_cndmask_b32_e32 v216, v216, v218, vcc
	v_cmp_gt_f32_e32 vcc, 0, v167
	v_rcp_f32_e32 v245, v245
	v_add_f32_e32 v184, v207, v184
	v_cndmask_b32_e32 v217, v217, v219, vcc
	v_pk_fma_f32 v[218:219], v[240:241], s[70:71], v[220:221] op_sel_hi:[1,0,0]
	v_pk_mul_f32 v[242:243], v[160:161], v[160:161]
	v_pk_fma_f32 v[218:219], v[240:241], v[218:219], s[74:75] op_sel_hi:[1,1,0]
	v_add_f32_e32 v184, v208, v184
	v_pk_fma_f32 v[218:219], v[240:241], v[218:219], s[76:77] op_sel_hi:[1,1,0]
	v_pk_mul_f32 v[242:243], v[242:243], s[80:81] op_sel_hi:[1,0]
	v_pk_fma_f32 v[218:219], v[240:241], v[218:219], s[78:79] op_sel_hi:[1,1,0]
	v_mul_f32_e32 v231, v207, v207
	v_add_f32_e32 v184, v209, v184
	v_exp_f32_e32 v242, v242
	v_exp_f32_e32 v243, v243
	v_pk_mul_f32 v[218:219], v[240:241], v[218:219]
	v_pk_mul_f32 v[240:241], v[162:163], v[162:163]
	v_fmac_f32_e32 v231, v206, v206
	v_add_f32_e32 v184, v210, v184
	v_pk_fma_f32 v[220:221], v[244:245], s[70:71], v[220:221] op_sel_hi:[1,0,0]
	v_pk_mul_f32 v[240:241], v[240:241], s[80:81] op_sel_hi:[1,0]
	v_fmac_f32_e32 v231, v208, v208
	v_add_f32_e32 v184, v211, v184
	v_pk_fma_f32 v[220:221], v[244:245], v[220:221], s[74:75] op_sel_hi:[1,1,0]
	v_exp_f32_e32 v240, v240
	v_exp_f32_e32 v241, v241
	v_fmac_f32_e32 v231, v209, v209
	v_add_f32_e32 v184, v212, v184
	v_pk_fma_f32 v[220:221], v[244:245], v[220:221], s[76:77] op_sel_hi:[1,1,0]
	v_fmac_f32_e32 v231, v210, v210
	v_add_f32_e32 v184, v213, v184
	v_pk_mul_f32 v[218:219], v[242:243], v[218:219]
	v_pk_fma_f32 v[220:221], v[244:245], v[220:221], s[78:79] op_sel_hi:[1,1,0]
	v_fmac_f32_e32 v231, v211, v211
	v_add_f32_e32 v184, v214, v184
	v_pk_mul_f32 v[242:243], v[160:161], v[218:219]
	v_pk_fma_f32 v[218:219], v[160:161], v[218:219], v[160:161] neg_lo:[1,0,0] neg_hi:[1,0,0]
	v_cmp_gt_f32_e32 vcc, 0, v160
	v_pk_mul_f32 v[220:221], v[244:245], v[220:221]
	v_fmac_f32_e32 v231, v212, v212
	v_add_f32_e32 v184, v215, v184
	v_cndmask_b32_e32 v218, v218, v242, vcc
	v_cmp_gt_f32_e32 vcc, 0, v161
	v_pk_mul_f32 v[220:221], v[240:241], v[220:221]
	v_fmac_f32_e32 v231, v213, v213
	v_add_f32_e32 v184, v216, v184
	v_cndmask_b32_e32 v219, v219, v243, vcc
	v_pk_mul_f32 v[240:241], v[162:163], v[220:221]
	v_pk_fma_f32 v[220:221], v[162:163], v[220:221], v[162:163] neg_lo:[1,0,0] neg_hi:[1,0,0]
	v_cmp_gt_f32_e32 vcc, 0, v162
	v_fmac_f32_e32 v231, v214, v214
	v_add_f32_e32 v184, v217, v184
	v_and_b32_e32 v239, 64, v229
	v_cndmask_b32_e32 v220, v220, v240, vcc
	v_cmp_gt_f32_e32 vcc, 0, v163
	v_fmac_f32_e32 v231, v215, v215
	v_add_f32_e32 v184, v218, v184
	v_xor_b32_e32 v199, 16, v229
	v_add_u32_e32 v239, 64, v239
	v_cndmask_b32_e32 v221, v221, v241, vcc
	v_fmac_f32_e32 v231, v216, v216
	v_add_f32_e32 v184, v219, v184
	v_cmp_lt_i32_e32 vcc, v199, v239
	v_fmac_f32_e32 v231, v217, v217
	v_add_f32_e32 v184, v220, v184
	v_cndmask_b32_e32 v199, v229, v199, vcc
	v_add_f32_e32 v184, v221, v184
	v_lshlrev_b32_e32 v199, 2, v199
	v_fmac_f32_e32 v231, v218, v218
	v_mov_b32_e32 v240, v184
	s_nop 1
	v_permlane16_swap_b32_e32 v184, v240
	s_nop 1
	v_fmac_f32_e32 v231, v219, v219
	v_fmac_f32_e32 v231, v220, v220
	v_fmac_f32_e32 v231, v221, v221
	v_mov_b32_e32 v241, v231
	s_nop 1
	v_permlane16_swap_b32_e32 v231, v241
	s_nop 1
	s_waitcnt lgkmcnt(1)
	v_add_f32_e32 v184, v184, v240
	v_xor_b32_e32 v240, 32, v229
	v_cmp_lt_i32_e32 vcc, v240, v239
	s_waitcnt lgkmcnt(0)
	v_add_f32_e32 v231, v231, v241
	v_cndmask_b32_e32 v199, v229, v240, vcc
	v_lshlrev_b32_e32 v239, 2, v199
	v_mov_b32_e32 v199, v184
	s_nop 1
	v_permlane32_swap_b32_e32 v184, v199
	s_nop 1
	v_mov_b32_e32 v239, v231
	s_nop 1
	v_permlane32_swap_b32_e32 v231, v239
	s_nop 1
	s_and_saveexec_b64 s[90:91], s[4:5]
	s_cbranch_execz .LBB0_589
	v_lshlrev_b64 v[240:241], 2, v[204:205]
	v_lshl_add_u64 v[242:243], s[14:15], 0, v[240:241]
	v_lshl_add_u64 v[240:241], s[52:53], 0, v[240:241]
	s_waitcnt lgkmcnt(1)
	v_add_f32_e32 v184, v184, v199
	s_waitcnt lgkmcnt(0)
	v_add_f32_e32 v199, v231, v239
	global_atomic_add_f32 v[240:241], v184, off
	global_atomic_add_f32 v[242:243], v199, off

.LBB0_593:
	v_lshlrev_b64 v[162:163], 11, v[204:205]
	v_lshl_add_u64 v[166:167], v[202:203], 0, v[162:163]
	v_cvt_pk_bf16_f32 v162, v206, v207
	s_waitcnt lgkmcnt(0)
	v_cvt_pk_bf16_f32 v163, v208, v209
	v_cvt_pk_bf16_f32 v164, v210, v211
	v_cvt_pk_bf16_f32 v165, v212, v213
	global_store_dwordx4 v[166:167], v[162:165], off
	v_or_b32_e32 v160, 48, v198
	v_ashrrev_i32_e32 v161, 31, v160
	v_fmamk_f32 v164, v238, 0x3a800000, v228
	v_rsq_f32_e32 v168, v164
	v_cvt_pk_bf16_f32 v162, v214, v215
	v_cvt_pk_bf16_f32 v163, v216, v217
	v_cvt_pk_bf16_f32 v164, v218, v219
	v_cvt_pk_bf16_f32 v165, v220, v221
	s_and_b64 vcc, exec, s[10:11]
	v_pk_fma_f32 v[142:143], v[142:143], v[168:169], v[46:47] op_sel_hi:[1,0,1]
	v_pk_fma_f32 v[140:141], v[140:141], v[168:169], v[44:45] op_sel_hi:[1,0,1]
	v_pk_fma_f32 v[138:139], v[138:139], v[168:169], v[42:43] op_sel_hi:[1,0,1]
	v_pk_fma_f32 v[136:137], v[136:137], v[168:169], v[40:41] op_sel_hi:[1,0,1]
	v_pk_fma_f32 v[134:135], v[134:135], v[168:169], v[38:39] op_sel_hi:[1,0,1]
	v_pk_fma_f32 v[132:133], v[132:133], v[168:169], v[36:37] op_sel_hi:[1,0,1]
	v_pk_fma_f32 v[130:131], v[130:131], v[168:169], v[34:35] op_sel_hi:[1,0,1]
	v_pk_fma_f32 v[128:129], v[128:129], v[168:169], v[32:33] op_sel_hi:[1,0,1]
	s_mov_b64 s[90:91], -1
	global_store_dwordx4 v[166:167], v[162:165], off offset:256
	s_cbranch_vccnz .LBB0_599
	s_and_b64 vcc, exec, s[8:9]
	v_mov_b32_e32 v165, v143
	v_mov_b32_e32 v164, v142
	v_mov_b32_e32 v163, v141
	v_mov_b32_e32 v162, v140
	v_mov_b32_e32 v169, v139
	v_mov_b32_e32 v168, v138
	v_mov_b32_e32 v167, v137
	v_mov_b32_e32 v166, v136
	v_mov_b32_e32 v173, v135
	v_mov_b32_e32 v172, v134
	v_mov_b32_e32 v171, v133
	v_mov_b32_e32 v170, v132
	v_mov_b32_e32 v205, v131
	v_mov_b32_e32 v204, v130
	v_mov_b32_e32 v175, v129
	v_mov_b32_e32 v174, v128
	s_cbranch_vccnz .LBB0_598
	v_and_b32_e32 v163, 0x7fffffff, v141
	v_and_b32_e32 v162, 0x7fffffff, v140
	v_pk_fma_f32 v[162:163], v[162:163], s[68:69], 1.0 op_sel_hi:[1,0,0]
	v_mov_b64_e32 v[204:205], s[72:73]
	v_rcp_f32_e32 v162, v162
	v_rcp_f32_e32 v163, v163
	v_pk_mul_f32 v[166:167], v[140:141], v[140:141]
	v_and_b32_e32 v169, 0x7fffffff, v143
	v_pk_mul_f32 v[166:167], v[166:167], s[80:81] op_sel_hi:[1,0]
	v_pk_fma_f32 v[164:165], v[162:163], s[70:71], v[204:205] op_sel_hi:[1,0,0]
	v_exp_f32_e32 v166, v166
	v_pk_fma_f32 v[164:165], v[162:163], v[164:165], s[74:75] op_sel_hi:[1,1,0]
	v_exp_f32_e32 v167, v167
	v_pk_fma_f32 v[164:165], v[162:163], v[164:165], s[76:77] op_sel_hi:[1,1,0]
	v_and_b32_e32 v168, 0x7fffffff, v142
	v_pk_fma_f32 v[164:165], v[162:163], v[164:165], s[78:79] op_sel_hi:[1,1,0]
	v_pk_fma_f32 v[168:169], v[168:169], s[68:69], 1.0 op_sel_hi:[1,0,0]
	v_pk_mul_f32 v[162:163], v[162:163], v[164:165]
	v_rcp_f32_e32 v168, v168
	v_rcp_f32_e32 v169, v169
	v_pk_mul_f32 v[162:163], v[166:167], v[162:163]
	v_cmp_gt_f32_e32 vcc, 0, v140
	v_pk_mul_f32 v[166:167], v[140:141], v[162:163]
	v_pk_fma_f32 v[162:163], v[140:141], v[162:163], v[140:141] neg_lo:[1,0,0] neg_hi:[1,0,0]
	v_pk_mul_f32 v[164:165], v[142:143], v[142:143]
	v_cndmask_b32_e32 v162, v162, v166, vcc
	v_cmp_gt_f32_e32 vcc, 0, v141
	v_pk_mul_f32 v[164:165], v[164:165], s[80:81] op_sel_hi:[1,0]
	v_pk_mul_f32 v[170:171], v[136:137], v[136:137]
	v_cndmask_b32_e32 v163, v163, v167, vcc
	v_pk_fma_f32 v[166:167], v[168:169], s[70:71], v[204:205] op_sel_hi:[1,0,0]
	v_exp_f32_e32 v164, v164
	v_pk_fma_f32 v[166:167], v[168:169], v[166:167], s[74:75] op_sel_hi:[1,1,0]
	v_exp_f32_e32 v165, v165
	v_pk_fma_f32 v[166:167], v[168:169], v[166:167], s[76:77] op_sel_hi:[1,1,0]
	v_cmp_gt_f32_e32 vcc, 0, v142
	v_pk_fma_f32 v[166:167], v[168:169], v[166:167], s[78:79] op_sel_hi:[1,1,0]
	v_pk_mul_f32 v[170:171], v[170:171], s[80:81] op_sel_hi:[1,0]
	v_pk_mul_f32 v[166:167], v[168:169], v[166:167]
	v_and_b32_e32 v169, 0x7fffffff, v137
	v_and_b32_e32 v168, 0x7fffffff, v136
	v_pk_fma_f32 v[168:169], v[168:169], s[68:69], 1.0 op_sel_hi:[1,0,0]
	v_pk_mul_f32 v[164:165], v[164:165], v[166:167]
	v_rcp_f32_e32 v168, v168
	v_rcp_f32_e32 v169, v169
	v_pk_mul_f32 v[166:167], v[142:143], v[164:165]
	v_pk_fma_f32 v[164:165], v[142:143], v[164:165], v[142:143] neg_lo:[1,0,0] neg_hi:[1,0,0]
	v_exp_f32_e32 v170, v170
	v_cndmask_b32_e32 v164, v164, v166, vcc
	v_cmp_gt_f32_e32 vcc, 0, v143
	v_exp_f32_e32 v171, v171
	v_and_b32_e32 v173, 0x7fffffff, v139
	v_cndmask_b32_e32 v165, v165, v167, vcc
	v_pk_fma_f32 v[166:167], v[168:169], s[70:71], v[204:205] op_sel_hi:[1,0,0]
	v_and_b32_e32 v172, 0x7fffffff, v138
	v_pk_fma_f32 v[166:167], v[168:169], v[166:167], s[74:75] op_sel_hi:[1,1,0]
	v_pk_fma_f32 v[172:173], v[172:173], s[68:69], 1.0 op_sel_hi:[1,0,0]
	v_pk_fma_f32 v[166:167], v[168:169], v[166:167], s[76:77] op_sel_hi:[1,1,0]
	v_rcp_f32_e32 v172, v172
	v_pk_fma_f32 v[166:167], v[168:169], v[166:167], s[78:79] op_sel_hi:[1,1,0]
	v_rcp_f32_e32 v173, v173
	v_pk_mul_f32 v[166:167], v[168:169], v[166:167]
	v_cmp_gt_f32_e32 vcc, 0, v136
	v_pk_mul_f32 v[166:167], v[170:171], v[166:167]
	v_pk_mul_f32 v[168:169], v[138:139], v[138:139]
	v_pk_mul_f32 v[170:171], v[136:137], v[166:167]
	v_pk_fma_f32 v[166:167], v[136:137], v[166:167], v[136:137] neg_lo:[1,0,0] neg_hi:[1,0,0]
	v_pk_mul_f32 v[168:169], v[168:169], s[80:81] op_sel_hi:[1,0]
	v_cndmask_b32_e32 v166, v166, v170, vcc
	v_cmp_gt_f32_e32 vcc, 0, v137
	v_exp_f32_e32 v168, v168
	v_exp_f32_e32 v169, v169
	v_cndmask_b32_e32 v167, v167, v171, vcc
	v_pk_fma_f32 v[170:171], v[172:173], s[70:71], v[204:205] op_sel_hi:[1,0,0]
	v_cmp_gt_f32_e32 vcc, 0, v138
	v_pk_fma_f32 v[170:171], v[172:173], v[170:171], s[74:75] op_sel_hi:[1,1,0]
	v_pk_mul_f32 v[174:175], v[132:133], v[132:133]
	v_pk_fma_f32 v[170:171], v[172:173], v[170:171], s[76:77] op_sel_hi:[1,1,0]
	v_pk_mul_f32 v[174:175], v[174:175], s[80:81] op_sel_hi:[1,0]
	v_pk_fma_f32 v[170:171], v[172:173], v[170:171], s[78:79] op_sel_hi:[1,1,0]
	v_exp_f32_e32 v174, v174
	v_pk_mul_f32 v[170:171], v[172:173], v[170:171]
	v_and_b32_e32 v173, 0x7fffffff, v133
	v_and_b32_e32 v172, 0x7fffffff, v132
	v_pk_fma_f32 v[172:173], v[172:173], s[68:69], 1.0 op_sel_hi:[1,0,0]
	v_pk_mul_f32 v[168:169], v[168:169], v[170:171]
	v_rcp_f32_e32 v172, v172
	v_rcp_f32_e32 v173, v173
	v_pk_mul_f32 v[170:171], v[138:139], v[168:169]
	v_pk_fma_f32 v[168:169], v[138:139], v[168:169], v[138:139] neg_lo:[1,0,0] neg_hi:[1,0,0]
	v_exp_f32_e32 v175, v175
	v_cndmask_b32_e32 v168, v168, v170, vcc
	v_cmp_gt_f32_e32 vcc, 0, v139
	v_and_b32_e32 v207, 0x7fffffff, v135
	v_and_b32_e32 v206, 0x7fffffff, v134
	v_cndmask_b32_e32 v169, v169, v171, vcc
	v_pk_fma_f32 v[170:171], v[172:173], s[70:71], v[204:205] op_sel_hi:[1,0,0]
	v_pk_fma_f32 v[206:207], v[206:207], s[68:69], 1.0 op_sel_hi:[1,0,0]
	v_pk_fma_f32 v[170:171], v[172:173], v[170:171], s[74:75] op_sel_hi:[1,1,0]
	v_rcp_f32_e32 v206, v206
	v_pk_fma_f32 v[170:171], v[172:173], v[170:171], s[76:77] op_sel_hi:[1,1,0]
	v_rcp_f32_e32 v207, v207
	v_pk_fma_f32 v[170:171], v[172:173], v[170:171], s[78:79] op_sel_hi:[1,1,0]
	v_cmp_gt_f32_e32 vcc, 0, v132
	v_pk_mul_f32 v[170:171], v[172:173], v[170:171]
	v_pk_mul_f32 v[172:173], v[134:135], v[134:135]
	v_pk_mul_f32 v[170:171], v[174:175], v[170:171]
	v_pk_mul_f32 v[172:173], v[172:173], s[80:81] op_sel_hi:[1,0]
	v_pk_mul_f32 v[174:175], v[132:133], v[170:171]
	v_pk_fma_f32 v[170:171], v[132:133], v[170:171], v[132:133] neg_lo:[1,0,0] neg_hi:[1,0,0]
	v_exp_f32_e32 v172, v172
	v_cndmask_b32_e32 v170, v170, v174, vcc
	v_cmp_gt_f32_e32 vcc, 0, v133
	v_exp_f32_e32 v173, v173
	v_and_b32_e32 v211, 0x7fffffff, v131
	v_cndmask_b32_e32 v171, v171, v175, vcc
	v_pk_fma_f32 v[174:175], v[206:207], s[70:71], v[204:205] op_sel_hi:[1,0,0]
	v_cmp_gt_f32_e32 vcc, 0, v134
	v_pk_fma_f32 v[174:175], v[206:207], v[174:175], s[74:75] op_sel_hi:[1,1,0]
	v_and_b32_e32 v210, 0x7fffffff, v130
	v_pk_fma_f32 v[174:175], v[206:207], v[174:175], s[76:77] op_sel_hi:[1,1,0]
	v_pk_fma_f32 v[210:211], v[210:211], s[68:69], 1.0 op_sel_hi:[1,0,0]
	v_pk_fma_f32 v[174:175], v[206:207], v[174:175], s[78:79] op_sel_hi:[1,1,0]
	v_rcp_f32_e32 v210, v210
	v_pk_mul_f32 v[174:175], v[206:207], v[174:175]
	v_and_b32_e32 v207, 0x7fffffff, v129
	v_and_b32_e32 v206, 0x7fffffff, v128
	v_pk_fma_f32 v[206:207], v[206:207], s[68:69], 1.0 op_sel_hi:[1,0,0]
	v_pk_mul_f32 v[172:173], v[172:173], v[174:175]
	v_rcp_f32_e32 v206, v206
	v_rcp_f32_e32 v207, v207
	v_pk_mul_f32 v[174:175], v[134:135], v[172:173]
	v_pk_fma_f32 v[172:173], v[134:135], v[172:173], v[134:135] neg_lo:[1,0,0] neg_hi:[1,0,0]
	v_rcp_f32_e32 v211, v211
	v_cndmask_b32_e32 v172, v172, v174, vcc
	v_cmp_gt_f32_e32 vcc, 0, v135
	v_pk_mul_f32 v[208:209], v[128:129], v[128:129]
	v_add_f32_e32 v184, 0, v162
	v_cndmask_b32_e32 v173, v173, v175, vcc
	v_pk_fma_f32 v[174:175], v[206:207], s[70:71], v[204:205] op_sel_hi:[1,0,0]
	v_pk_mul_f32 v[208:209], v[208:209], s[80:81] op_sel_hi:[1,0]
	v_pk_fma_f32 v[174:175], v[206:207], v[174:175], s[74:75] op_sel_hi:[1,1,0]
	v_exp_f32_e32 v208, v208
	v_pk_fma_f32 v[174:175], v[206:207], v[174:175], s[76:77] op_sel_hi:[1,1,0]
	v_exp_f32_e32 v209, v209
	v_pk_fma_f32 v[174:175], v[206:207], v[174:175], s[78:79] op_sel_hi:[1,1,0]
	v_pk_fma_f32 v[204:205], v[210:211], s[70:71], v[204:205] op_sel_hi:[1,0,0]
	v_pk_mul_f32 v[174:175], v[206:207], v[174:175]
	v_pk_mul_f32 v[206:207], v[130:131], v[130:131]
	v_pk_fma_f32 v[204:205], v[210:211], v[204:205], s[74:75] op_sel_hi:[1,1,0]
	v_pk_mul_f32 v[206:207], v[206:207], s[80:81] op_sel_hi:[1,0]
	v_pk_fma_f32 v[204:205], v[210:211], v[204:205], s[76:77] op_sel_hi:[1,1,0]
	v_exp_f32_e32 v206, v206
	v_exp_f32_e32 v207, v207
	v_pk_mul_f32 v[174:175], v[208:209], v[174:175]
	v_pk_fma_f32 v[204:205], v[210:211], v[204:205], s[78:79] op_sel_hi:[1,1,0]
	v_pk_mul_f32 v[208:209], v[128:129], v[174:175]
	v_pk_fma_f32 v[174:175], v[128:129], v[174:175], v[128:129] neg_lo:[1,0,0] neg_hi:[1,0,0]
	v_cmp_gt_f32_e32 vcc, 0, v128
	v_pk_mul_f32 v[204:205], v[210:211], v[204:205]
	v_add_f32_e32 v184, v163, v184
	v_cndmask_b32_e32 v174, v174, v208, vcc
	v_cmp_gt_f32_e32 vcc, 0, v129
	v_pk_mul_f32 v[204:205], v[206:207], v[204:205]
	v_add_f32_e32 v184, v164, v184
	v_cndmask_b32_e32 v175, v175, v209, vcc
	v_pk_mul_f32 v[206:207], v[130:131], v[204:205]
	v_pk_fma_f32 v[204:205], v[130:131], v[204:205], v[130:131] neg_lo:[1,0,0] neg_hi:[1,0,0]
	v_cmp_gt_f32_e32 vcc, 0, v130
	v_add_f32_e32 v184, v165, v184
	v_add_f32_e32 v184, v166, v184
	v_cndmask_b32_e32 v204, v204, v206, vcc
	v_mul_f32_e32 v206, v163, v163
	v_fmac_f32_e32 v206, v162, v162
	v_fmac_f32_e32 v206, v164, v164
	v_add_f32_e32 v184, v167, v184
	v_fmac_f32_e32 v206, v165, v165
	v_add_f32_e32 v184, v168, v184
	v_fmac_f32_e32 v206, v166, v166
	v_add_f32_e32 v184, v169, v184
	v_fmac_f32_e32 v206, v167, v167
	v_add_f32_e32 v184, v170, v184
	v_fmac_f32_e32 v206, v168, v168
	v_add_f32_e32 v184, v171, v184
	v_cmp_gt_f32_e32 vcc, 0, v131
	v_fmac_f32_e32 v206, v169, v169
	v_add_f32_e32 v184, v172, v184
	v_cndmask_b32_e32 v205, v205, v207, vcc
	v_fmac_f32_e32 v206, v170, v170
	v_add_f32_e32 v184, v173, v184
	v_and_b32_e32 v207, 64, v229
	v_fmac_f32_e32 v206, v171, v171
	v_add_f32_e32 v184, v174, v184
	v_xor_b32_e32 v199, 16, v229
	v_add_u32_e32 v207, 64, v207
	v_fmac_f32_e32 v206, v172, v172
	v_add_f32_e32 v184, v175, v184
	v_cmp_lt_i32_e32 vcc, v199, v207
	v_fmac_f32_e32 v206, v173, v173
	v_add_f32_e32 v184, v204, v184
	v_cndmask_b32_e32 v199, v229, v199, vcc
	v_add_f32_e32 v184, v205, v184
	v_lshlrev_b32_e32 v199, 2, v199
	v_fmac_f32_e32 v206, v174, v174
	v_mov_b32_e32 v208, v184
	s_nop 1
	v_permlane16_swap_b32_e32 v184, v208
	s_nop 1
	v_fmac_f32_e32 v206, v175, v175
	v_fmac_f32_e32 v206, v204, v204
	v_fmac_f32_e32 v206, v205, v205
	v_mov_b32_e32 v209, v206
	s_nop 1
	v_permlane16_swap_b32_e32 v206, v209
	s_nop 1
	s_waitcnt lgkmcnt(1)
	v_add_f32_e32 v184, v184, v208
	v_xor_b32_e32 v208, 32, v229
	v_cmp_lt_i32_e32 vcc, v208, v207
	s_waitcnt lgkmcnt(0)
	v_add_f32_e32 v206, v206, v209
	v_cndmask_b32_e32 v199, v229, v208, vcc
	v_lshlrev_b32_e32 v207, 2, v199
	v_mov_b32_e32 v199, v184
	s_nop 1
	v_permlane32_swap_b32_e32 v184, v199
	s_nop 1
	v_mov_b32_e32 v207, v206
	s_nop 1
	v_permlane32_swap_b32_e32 v206, v207
	s_nop 1
	s_and_saveexec_b64 s[90:91], s[4:5]
	s_cbranch_execz .LBB0_597
	v_lshlrev_b64 v[208:209], 2, v[160:161]
	v_lshl_add_u64 v[210:211], s[14:15], 0, v[208:209]
	v_lshl_add_u64 v[208:209], s[52:53], 0, v[208:209]
	s_waitcnt lgkmcnt(1)
	v_add_f32_e32 v184, v184, v199
	s_waitcnt lgkmcnt(0)
	v_add_f32_e32 v199, v206, v207
	global_atomic_add_f32 v[208:209], v184, off
	global_atomic_add_f32 v[210:211], v199, off

.LBB0_603:
	s_nop 0
	v_fmamk_f32 v128, v237, 0x3a800000, v228
	v_rsq_f32_e32 v130, v128
	v_add_u32_e32 v128, 0x80, v198
	v_ashrrev_i32_e32 v129, 31, v128
	s_and_b64 vcc, exec, s[10:11]
	v_pk_fma_f32 v[94:95], v[94:95], v[130:131], v[46:47] op_sel_hi:[1,0,1]
	v_pk_fma_f32 v[92:93], v[92:93], v[130:131], v[44:45] op_sel_hi:[1,0,1]
	v_pk_fma_f32 v[90:91], v[90:91], v[130:131], v[42:43] op_sel_hi:[1,0,1]
	v_pk_fma_f32 v[88:89], v[88:89], v[130:131], v[40:41] op_sel_hi:[1,0,1]
	v_pk_fma_f32 v[74:75], v[74:75], v[130:131], v[38:39] op_sel_hi:[1,0,1]
	v_pk_fma_f32 v[72:73], v[72:73], v[130:131], v[36:37] op_sel_hi:[1,0,1]
	v_pk_fma_f32 v[70:71], v[70:71], v[130:131], v[34:35] op_sel_hi:[1,0,1]
	v_pk_fma_f32 v[68:69], v[68:69], v[130:131], v[32:33] op_sel_hi:[1,0,1]
	s_mov_b64 s[90:91], -1
	s_cbranch_vccnz .LBB0_609
	s_and_b64 vcc, exec, s[8:9]
	v_mov_b32_e32 v133, v95
	v_mov_b32_e32 v132, v94
	v_mov_b32_e32 v131, v93
	v_mov_b32_e32 v130, v92
	v_mov_b32_e32 v137, v91
	v_mov_b32_e32 v136, v90
	v_mov_b32_e32 v135, v89
	v_mov_b32_e32 v134, v88
	v_mov_b32_e32 v141, v75
	v_mov_b32_e32 v140, v74
	v_mov_b32_e32 v139, v73
	v_mov_b32_e32 v138, v72
	v_mov_b32_e32 v161, v71
	v_mov_b32_e32 v160, v70
	v_mov_b32_e32 v143, v69
	v_mov_b32_e32 v142, v68
	s_cbranch_vccnz .LBB0_608
	v_and_b32_e32 v131, 0x7fffffff, v93
	v_and_b32_e32 v130, 0x7fffffff, v92
	v_pk_fma_f32 v[130:131], v[130:131], s[68:69], 1.0 op_sel_hi:[1,0,0]
	v_mov_b64_e32 v[160:161], s[72:73]
	v_rcp_f32_e32 v130, v130
	v_rcp_f32_e32 v131, v131
	v_pk_mul_f32 v[134:135], v[92:93], v[92:93]
	v_and_b32_e32 v137, 0x7fffffff, v95
	v_pk_mul_f32 v[134:135], v[134:135], s[80:81] op_sel_hi:[1,0]
	v_pk_fma_f32 v[132:133], v[130:131], s[70:71], v[160:161] op_sel_hi:[1,0,0]
	v_exp_f32_e32 v134, v134
	v_pk_fma_f32 v[132:133], v[130:131], v[132:133], s[74:75] op_sel_hi:[1,1,0]
	v_exp_f32_e32 v135, v135
	v_pk_fma_f32 v[132:133], v[130:131], v[132:133], s[76:77] op_sel_hi:[1,1,0]
	v_and_b32_e32 v136, 0x7fffffff, v94
	v_pk_fma_f32 v[132:133], v[130:131], v[132:133], s[78:79] op_sel_hi:[1,1,0]
	v_pk_fma_f32 v[136:137], v[136:137], s[68:69], 1.0 op_sel_hi:[1,0,0]
	v_pk_mul_f32 v[130:131], v[130:131], v[132:133]
	v_rcp_f32_e32 v136, v136
	v_rcp_f32_e32 v137, v137
	v_pk_mul_f32 v[130:131], v[134:135], v[130:131]
	v_cmp_gt_f32_e32 vcc, 0, v92
	v_pk_mul_f32 v[134:135], v[92:93], v[130:131]
	v_pk_fma_f32 v[130:131], v[92:93], v[130:131], v[92:93] neg_lo:[1,0,0] neg_hi:[1,0,0]
	v_pk_mul_f32 v[132:133], v[94:95], v[94:95]
	v_cndmask_b32_e32 v130, v130, v134, vcc
	v_cmp_gt_f32_e32 vcc, 0, v93
	v_pk_mul_f32 v[132:133], v[132:133], s[80:81] op_sel_hi:[1,0]
	v_pk_mul_f32 v[138:139], v[88:89], v[88:89]
	v_cndmask_b32_e32 v131, v131, v135, vcc
	v_pk_fma_f32 v[134:135], v[136:137], s[70:71], v[160:161] op_sel_hi:[1,0,0]
	v_exp_f32_e32 v132, v132
	v_pk_fma_f32 v[134:135], v[136:137], v[134:135], s[74:75] op_sel_hi:[1,1,0]
	v_exp_f32_e32 v133, v133
	v_pk_fma_f32 v[134:135], v[136:137], v[134:135], s[76:77] op_sel_hi:[1,1,0]
	v_cmp_gt_f32_e32 vcc, 0, v94
	v_pk_fma_f32 v[134:135], v[136:137], v[134:135], s[78:79] op_sel_hi:[1,1,0]
	v_pk_mul_f32 v[138:139], v[138:139], s[80:81] op_sel_hi:[1,0]
	v_pk_mul_f32 v[134:135], v[136:137], v[134:135]
	v_and_b32_e32 v137, 0x7fffffff, v89
	v_and_b32_e32 v136, 0x7fffffff, v88
	v_pk_fma_f32 v[136:137], v[136:137], s[68:69], 1.0 op_sel_hi:[1,0,0]
	v_pk_mul_f32 v[132:133], v[132:133], v[134:135]
	v_rcp_f32_e32 v136, v136
	v_rcp_f32_e32 v137, v137
	v_pk_mul_f32 v[134:135], v[94:95], v[132:133]
	v_pk_fma_f32 v[132:133], v[94:95], v[132:133], v[94:95] neg_lo:[1,0,0] neg_hi:[1,0,0]
	v_exp_f32_e32 v138, v138
	v_cndmask_b32_e32 v132, v132, v134, vcc
	v_cmp_gt_f32_e32 vcc, 0, v95
	v_exp_f32_e32 v139, v139
	v_and_b32_e32 v141, 0x7fffffff, v91
	v_cndmask_b32_e32 v133, v133, v135, vcc
	v_pk_fma_f32 v[134:135], v[136:137], s[70:71], v[160:161] op_sel_hi:[1,0,0]
	v_and_b32_e32 v140, 0x7fffffff, v90
	v_pk_fma_f32 v[134:135], v[136:137], v[134:135], s[74:75] op_sel_hi:[1,1,0]
	v_pk_fma_f32 v[140:141], v[140:141], s[68:69], 1.0 op_sel_hi:[1,0,0]
	v_pk_fma_f32 v[134:135], v[136:137], v[134:135], s[76:77] op_sel_hi:[1,1,0]
	v_rcp_f32_e32 v140, v140
	v_pk_fma_f32 v[134:135], v[136:137], v[134:135], s[78:79] op_sel_hi:[1,1,0]
	v_rcp_f32_e32 v141, v141
	v_pk_mul_f32 v[134:135], v[136:137], v[134:135]
	v_cmp_gt_f32_e32 vcc, 0, v88
	v_pk_mul_f32 v[134:135], v[138:139], v[134:135]
	v_pk_mul_f32 v[136:137], v[90:91], v[90:91]
	v_pk_mul_f32 v[138:139], v[88:89], v[134:135]
	v_pk_fma_f32 v[134:135], v[88:89], v[134:135], v[88:89] neg_lo:[1,0,0] neg_hi:[1,0,0]
	v_pk_mul_f32 v[136:137], v[136:137], s[80:81] op_sel_hi:[1,0]
	v_cndmask_b32_e32 v134, v134, v138, vcc
	v_cmp_gt_f32_e32 vcc, 0, v89
	v_exp_f32_e32 v136, v136
	v_exp_f32_e32 v137, v137
	v_cndmask_b32_e32 v135, v135, v139, vcc
	v_pk_fma_f32 v[138:139], v[140:141], s[70:71], v[160:161] op_sel_hi:[1,0,0]
	v_cmp_gt_f32_e32 vcc, 0, v90
	v_pk_fma_f32 v[138:139], v[140:141], v[138:139], s[74:75] op_sel_hi:[1,1,0]
	v_pk_mul_f32 v[142:143], v[72:73], v[72:73]
	v_pk_fma_f32 v[138:139], v[140:141], v[138:139], s[76:77] op_sel_hi:[1,1,0]
	v_pk_mul_f32 v[142:143], v[142:143], s[80:81] op_sel_hi:[1,0]
	v_pk_fma_f32 v[138:139], v[140:141], v[138:139], s[78:79] op_sel_hi:[1,1,0]
	v_exp_f32_e32 v142, v142
	v_pk_mul_f32 v[138:139], v[140:141], v[138:139]
	v_and_b32_e32 v141, 0x7fffffff, v73
	v_and_b32_e32 v140, 0x7fffffff, v72
	v_pk_fma_f32 v[140:141], v[140:141], s[68:69], 1.0 op_sel_hi:[1,0,0]
	v_pk_mul_f32 v[136:137], v[136:137], v[138:139]
	v_rcp_f32_e32 v140, v140
	v_rcp_f32_e32 v141, v141
	v_pk_mul_f32 v[138:139], v[90:91], v[136:137]
	v_pk_fma_f32 v[136:137], v[90:91], v[136:137], v[90:91] neg_lo:[1,0,0] neg_hi:[1,0,0]
	v_exp_f32_e32 v143, v143
	v_cndmask_b32_e32 v136, v136, v138, vcc
	v_cmp_gt_f32_e32 vcc, 0, v91
	v_and_b32_e32 v163, 0x7fffffff, v75
	v_and_b32_e32 v162, 0x7fffffff, v74
	v_cndmask_b32_e32 v137, v137, v139, vcc
	v_pk_fma_f32 v[138:139], v[140:141], s[70:71], v[160:161] op_sel_hi:[1,0,0]
	v_pk_fma_f32 v[162:163], v[162:163], s[68:69], 1.0 op_sel_hi:[1,0,0]
	v_pk_fma_f32 v[138:139], v[140:141], v[138:139], s[74:75] op_sel_hi:[1,1,0]
	v_rcp_f32_e32 v162, v162
	v_pk_fma_f32 v[138:139], v[140:141], v[138:139], s[76:77] op_sel_hi:[1,1,0]
	v_rcp_f32_e32 v163, v163
	v_pk_fma_f32 v[138:139], v[140:141], v[138:139], s[78:79] op_sel_hi:[1,1,0]
	v_cmp_gt_f32_e32 vcc, 0, v72
	v_pk_mul_f32 v[138:139], v[140:141], v[138:139]
	v_pk_mul_f32 v[140:141], v[74:75], v[74:75]
	v_pk_mul_f32 v[138:139], v[142:143], v[138:139]
	v_pk_mul_f32 v[140:141], v[140:141], s[80:81] op_sel_hi:[1,0]
	v_pk_mul_f32 v[142:143], v[72:73], v[138:139]
	v_pk_fma_f32 v[138:139], v[72:73], v[138:139], v[72:73] neg_lo:[1,0,0] neg_hi:[1,0,0]
	v_exp_f32_e32 v140, v140
	v_cndmask_b32_e32 v138, v138, v142, vcc
	v_cmp_gt_f32_e32 vcc, 0, v73
	v_exp_f32_e32 v141, v141
	v_and_b32_e32 v167, 0x7fffffff, v71
	v_cndmask_b32_e32 v139, v139, v143, vcc
	v_pk_fma_f32 v[142:143], v[162:163], s[70:71], v[160:161] op_sel_hi:[1,0,0]
	v_cmp_gt_f32_e32 vcc, 0, v74
	v_pk_fma_f32 v[142:143], v[162:163], v[142:143], s[74:75] op_sel_hi:[1,1,0]
	v_and_b32_e32 v166, 0x7fffffff, v70
	v_pk_fma_f32 v[142:143], v[162:163], v[142:143], s[76:77] op_sel_hi:[1,1,0]
	v_pk_fma_f32 v[166:167], v[166:167], s[68:69], 1.0 op_sel_hi:[1,0,0]
	v_pk_fma_f32 v[142:143], v[162:163], v[142:143], s[78:79] op_sel_hi:[1,1,0]
	v_rcp_f32_e32 v166, v166
	v_pk_mul_f32 v[142:143], v[162:163], v[142:143]
	v_and_b32_e32 v163, 0x7fffffff, v69
	v_and_b32_e32 v162, 0x7fffffff, v68
	v_pk_fma_f32 v[162:163], v[162:163], s[68:69], 1.0 op_sel_hi:[1,0,0]
	v_pk_mul_f32 v[140:141], v[140:141], v[142:143]
	v_rcp_f32_e32 v162, v162
	v_rcp_f32_e32 v163, v163
	v_pk_mul_f32 v[142:143], v[74:75], v[140:141]
	v_pk_fma_f32 v[140:141], v[74:75], v[140:141], v[74:75] neg_lo:[1,0,0] neg_hi:[1,0,0]
	v_rcp_f32_e32 v167, v167
	v_cndmask_b32_e32 v140, v140, v142, vcc
	v_cmp_gt_f32_e32 vcc, 0, v75
	v_pk_mul_f32 v[164:165], v[68:69], v[68:69]
	s_nop 0
	v_cndmask_b32_e32 v141, v141, v143, vcc
	v_pk_fma_f32 v[142:143], v[162:163], s[70:71], v[160:161] op_sel_hi:[1,0,0]
	v_pk_mul_f32 v[164:165], v[164:165], s[80:81] op_sel_hi:[1,0]
	v_pk_fma_f32 v[142:143], v[162:163], v[142:143], s[74:75] op_sel_hi:[1,1,0]
	v_exp_f32_e32 v164, v164
	v_pk_fma_f32 v[142:143], v[162:163], v[142:143], s[76:77] op_sel_hi:[1,1,0]
	v_exp_f32_e32 v165, v165
	v_pk_fma_f32 v[142:143], v[162:163], v[142:143], s[78:79] op_sel_hi:[1,1,0]
	v_pk_fma_f32 v[160:161], v[166:167], s[70:71], v[160:161] op_sel_hi:[1,0,0]
	v_pk_mul_f32 v[142:143], v[162:163], v[142:143]
	v_pk_mul_f32 v[162:163], v[70:71], v[70:71]
	v_pk_fma_f32 v[160:161], v[166:167], v[160:161], s[74:75] op_sel_hi:[1,1,0]
	v_pk_mul_f32 v[162:163], v[162:163], s[80:81] op_sel_hi:[1,0]
	v_pk_fma_f32 v[160:161], v[166:167], v[160:161], s[76:77] op_sel_hi:[1,1,0]
	v_exp_f32_e32 v162, v162
	v_exp_f32_e32 v163, v163
	v_pk_mul_f32 v[142:143], v[164:165], v[142:143]
	v_pk_fma_f32 v[160:161], v[166:167], v[160:161], s[78:79] op_sel_hi:[1,1,0]
	v_pk_mul_f32 v[164:165], v[68:69], v[142:143]
	v_pk_fma_f32 v[142:143], v[68:69], v[142:143], v[68:69] neg_lo:[1,0,0] neg_hi:[1,0,0]
	v_cmp_gt_f32_e32 vcc, 0, v68
	v_pk_mul_f32 v[160:161], v[166:167], v[160:161]
	s_nop 0
	v_cndmask_b32_e32 v142, v142, v164, vcc
	v_cmp_gt_f32_e32 vcc, 0, v69
	v_pk_mul_f32 v[160:161], v[162:163], v[160:161]
	v_mul_f32_e32 v164, v131, v131
	v_cndmask_b32_e32 v143, v143, v165, vcc
	v_pk_mul_f32 v[162:163], v[70:71], v[160:161]
	v_pk_fma_f32 v[160:161], v[70:71], v[160:161], v[70:71] neg_lo:[1,0,0] neg_hi:[1,0,0]
	v_cmp_gt_f32_e32 vcc, 0, v70
	v_fmac_f32_e32 v164, v130, v130
	v_fmac_f32_e32 v164, v132, v132
	v_cndmask_b32_e32 v160, v160, v162, vcc
	v_add_f32_e32 v162, 0, v130
	v_add_f32_e32 v162, v131, v162
	v_add_f32_e32 v162, v132, v162
	v_add_f32_e32 v162, v133, v162
	v_add_f32_e32 v162, v134, v162
	v_add_f32_e32 v162, v135, v162
	v_fmac_f32_e32 v164, v133, v133
	v_add_f32_e32 v162, v136, v162
	v_fmac_f32_e32 v164, v134, v134
	v_add_f32_e32 v162, v137, v162
	v_fmac_f32_e32 v164, v135, v135
	v_add_f32_e32 v162, v138, v162
	v_fmac_f32_e32 v164, v136, v136
	v_add_f32_e32 v162, v139, v162
	v_fmac_f32_e32 v164, v137, v137
	v_add_f32_e32 v162, v140, v162
	v_cmp_gt_f32_e32 vcc, 0, v71
	v_fmac_f32_e32 v164, v138, v138
	v_add_f32_e32 v162, v141, v162
	v_and_b32_e32 v165, 64, v229
	v_cndmask_b32_e32 v161, v161, v163, vcc
	v_fmac_f32_e32 v164, v139, v139
	v_add_f32_e32 v162, v142, v162
	v_xor_b32_e32 v163, 16, v229
	v_add_u32_e32 v165, 64, v165
	v_fmac_f32_e32 v164, v140, v140
	v_add_f32_e32 v162, v143, v162
	v_cmp_lt_i32_e32 vcc, v163, v165
	v_fmac_f32_e32 v164, v141, v141
	v_add_f32_e32 v162, v160, v162
	v_cndmask_b32_e32 v163, v229, v163, vcc
	v_add_f32_e32 v162, v161, v162
	v_lshlrev_b32_e32 v163, 2, v163
	v_fmac_f32_e32 v164, v142, v142
	v_mov_b32_e32 v166, v162
	s_nop 1
	v_permlane16_swap_b32_e32 v162, v166
	s_nop 1
	v_fmac_f32_e32 v164, v143, v143
	v_fmac_f32_e32 v164, v160, v160
	v_fmac_f32_e32 v164, v161, v161
	v_mov_b32_e32 v167, v164
	s_nop 1
	v_permlane16_swap_b32_e32 v164, v167
	s_nop 1
	s_waitcnt lgkmcnt(1)
	v_add_f32_e32 v162, v162, v166
	v_xor_b32_e32 v166, 32, v229
	v_cmp_lt_i32_e32 vcc, v166, v165
	s_waitcnt lgkmcnt(0)
	v_add_f32_e32 v164, v164, v167
	v_cndmask_b32_e32 v163, v229, v166, vcc
	v_lshlrev_b32_e32 v165, 2, v163
	v_mov_b32_e32 v163, v162
	s_nop 1
	v_permlane32_swap_b32_e32 v162, v163
	s_nop 1
	v_mov_b32_e32 v165, v164
	s_nop 1
	v_permlane32_swap_b32_e32 v164, v165
	s_nop 1
	s_and_saveexec_b64 s[90:91], s[4:5]
	s_cbranch_execz .LBB0_607
	v_lshlrev_b64 v[166:167], 2, v[128:129]
	v_lshl_add_u64 v[168:169], s[14:15], 0, v[166:167]
	v_lshl_add_u64 v[166:167], s[52:53], 0, v[166:167]
	s_waitcnt lgkmcnt(1)
	v_add_f32_e32 v162, v162, v163
	s_waitcnt lgkmcnt(0)
	v_add_f32_e32 v163, v164, v165
	global_atomic_add_f32 v[166:167], v162, off
	global_atomic_add_f32 v[168:169], v163, off

.LBB0_611:
	v_lshlrev_b64 v[70:71], 11, v[128:129]
	v_lshl_add_u64 v[74:75], v[202:203], 0, v[70:71]
	v_cvt_pk_bf16_f32 v70, v130, v131
	v_cvt_pk_bf16_f32 v71, v132, v133
	v_cvt_pk_bf16_f32 v72, v134, v135
	v_cvt_pk_bf16_f32 v73, v136, v137
	global_store_dwordx4 v[74:75], v[70:73], off
	v_add_u32_e32 v68, 0x90, v198
	v_ashrrev_i32_e32 v69, 31, v68
	v_fmamk_f32 v72, v236, 0x3a800000, v228
	v_rsq_f32_e32 v88, v72
	v_cvt_pk_bf16_f32 v70, v138, v139
	v_cvt_pk_bf16_f32 v71, v140, v141
	v_cvt_pk_bf16_f32 v72, v142, v143
	v_cvt_pk_bf16_f32 v73, v160, v161
	s_and_b64 vcc, exec, s[10:11]
	v_pk_fma_f32 v[62:63], v[62:63], v[88:89], v[46:47] op_sel_hi:[1,0,1]
	v_pk_fma_f32 v[60:61], v[60:61], v[88:89], v[44:45] op_sel_hi:[1,0,1]
	v_pk_fma_f32 v[58:59], v[58:59], v[88:89], v[42:43] op_sel_hi:[1,0,1]
	v_pk_fma_f32 v[56:57], v[56:57], v[88:89], v[40:41] op_sel_hi:[1,0,1]
	v_pk_fma_f32 v[54:55], v[54:55], v[88:89], v[38:39] op_sel_hi:[1,0,1]
	v_pk_fma_f32 v[52:53], v[52:53], v[88:89], v[36:37] op_sel_hi:[1,0,1]
	v_pk_fma_f32 v[50:51], v[50:51], v[88:89], v[34:35] op_sel_hi:[1,0,1]
	v_pk_fma_f32 v[48:49], v[48:49], v[88:89], v[32:33] op_sel_hi:[1,0,1]
	s_mov_b64 s[90:91], -1
	global_store_dwordx4 v[74:75], v[70:73], off offset:256
	s_cbranch_vccnz .LBB0_617
	s_and_b64 vcc, exec, s[8:9]
	v_mov_b32_e32 v73, v63
	v_mov_b32_e32 v72, v62
	v_mov_b32_e32 v71, v61
	v_mov_b32_e32 v70, v60
	v_mov_b32_e32 v89, v59
	v_mov_b32_e32 v88, v58
	v_mov_b32_e32 v75, v57
	v_mov_b32_e32 v74, v56
	v_mov_b32_e32 v93, v55
	v_mov_b32_e32 v92, v54
	v_mov_b32_e32 v91, v53
	v_mov_b32_e32 v90, v52
	s_waitcnt vmcnt(9)
	v_mov_b32_e32 v113, v51
	v_mov_b32_e32 v112, v50
	v_mov_b32_e32 v95, v49
	v_mov_b32_e32 v94, v48
	s_cbranch_vccnz .LBB0_616
	v_and_b32_e32 v71, 0x7fffffff, v61
	v_and_b32_e32 v70, 0x7fffffff, v60
	v_pk_fma_f32 v[70:71], v[70:71], s[68:69], 1.0 op_sel_hi:[1,0,0]
	v_mov_b64_e32 v[112:113], s[72:73]
	v_rcp_f32_e32 v70, v70
	v_rcp_f32_e32 v71, v71
	v_pk_mul_f32 v[74:75], v[60:61], v[60:61]
	v_and_b32_e32 v89, 0x7fffffff, v63
	v_pk_mul_f32 v[74:75], v[74:75], s[80:81] op_sel_hi:[1,0]
	v_pk_fma_f32 v[72:73], v[70:71], s[70:71], v[112:113] op_sel_hi:[1,0,0]
	v_exp_f32_e32 v74, v74
	v_pk_fma_f32 v[72:73], v[70:71], v[72:73], s[74:75] op_sel_hi:[1,1,0]
	v_exp_f32_e32 v75, v75
	v_pk_fma_f32 v[72:73], v[70:71], v[72:73], s[76:77] op_sel_hi:[1,1,0]
	v_and_b32_e32 v88, 0x7fffffff, v62
	v_pk_fma_f32 v[72:73], v[70:71], v[72:73], s[78:79] op_sel_hi:[1,1,0]
	v_pk_fma_f32 v[88:89], v[88:89], s[68:69], 1.0 op_sel_hi:[1,0,0]
	v_pk_mul_f32 v[70:71], v[70:71], v[72:73]
	v_rcp_f32_e32 v88, v88
	v_rcp_f32_e32 v89, v89
	v_pk_mul_f32 v[70:71], v[74:75], v[70:71]
	v_cmp_gt_f32_e32 vcc, 0, v60
	v_pk_mul_f32 v[74:75], v[60:61], v[70:71]
	v_pk_fma_f32 v[70:71], v[60:61], v[70:71], v[60:61] neg_lo:[1,0,0] neg_hi:[1,0,0]
	v_pk_mul_f32 v[72:73], v[62:63], v[62:63]
	v_cndmask_b32_e32 v70, v70, v74, vcc
	v_cmp_gt_f32_e32 vcc, 0, v61
	v_pk_mul_f32 v[72:73], v[72:73], s[80:81] op_sel_hi:[1,0]
	v_pk_mul_f32 v[90:91], v[56:57], v[56:57]
	v_cndmask_b32_e32 v71, v71, v75, vcc
	v_pk_fma_f32 v[74:75], v[88:89], s[70:71], v[112:113] op_sel_hi:[1,0,0]
	v_exp_f32_e32 v72, v72
	v_pk_fma_f32 v[74:75], v[88:89], v[74:75], s[74:75] op_sel_hi:[1,1,0]
	v_exp_f32_e32 v73, v73
	v_pk_fma_f32 v[74:75], v[88:89], v[74:75], s[76:77] op_sel_hi:[1,1,0]
	v_cmp_gt_f32_e32 vcc, 0, v62
	v_pk_fma_f32 v[74:75], v[88:89], v[74:75], s[78:79] op_sel_hi:[1,1,0]
	v_pk_mul_f32 v[90:91], v[90:91], s[80:81] op_sel_hi:[1,0]
	v_pk_mul_f32 v[74:75], v[88:89], v[74:75]
	v_and_b32_e32 v89, 0x7fffffff, v57
	v_and_b32_e32 v88, 0x7fffffff, v56
	v_pk_fma_f32 v[88:89], v[88:89], s[68:69], 1.0 op_sel_hi:[1,0,0]
	v_pk_mul_f32 v[72:73], v[72:73], v[74:75]
	v_rcp_f32_e32 v88, v88
	v_rcp_f32_e32 v89, v89
	v_pk_mul_f32 v[74:75], v[62:63], v[72:73]
	v_pk_fma_f32 v[72:73], v[62:63], v[72:73], v[62:63] neg_lo:[1,0,0] neg_hi:[1,0,0]
	v_exp_f32_e32 v90, v90
	v_cndmask_b32_e32 v72, v72, v74, vcc
	v_cmp_gt_f32_e32 vcc, 0, v63
	v_exp_f32_e32 v91, v91
	v_and_b32_e32 v93, 0x7fffffff, v59
	v_cndmask_b32_e32 v73, v73, v75, vcc
	v_pk_fma_f32 v[74:75], v[88:89], s[70:71], v[112:113] op_sel_hi:[1,0,0]
	v_and_b32_e32 v92, 0x7fffffff, v58
	v_pk_fma_f32 v[74:75], v[88:89], v[74:75], s[74:75] op_sel_hi:[1,1,0]
	v_pk_fma_f32 v[92:93], v[92:93], s[68:69], 1.0 op_sel_hi:[1,0,0]
	v_pk_fma_f32 v[74:75], v[88:89], v[74:75], s[76:77] op_sel_hi:[1,1,0]
	v_rcp_f32_e32 v92, v92
	v_pk_fma_f32 v[74:75], v[88:89], v[74:75], s[78:79] op_sel_hi:[1,1,0]
	v_rcp_f32_e32 v93, v93
	v_pk_mul_f32 v[74:75], v[88:89], v[74:75]
	v_cmp_gt_f32_e32 vcc, 0, v56
	v_pk_mul_f32 v[74:75], v[90:91], v[74:75]
	v_pk_mul_f32 v[88:89], v[58:59], v[58:59]
	v_pk_mul_f32 v[90:91], v[56:57], v[74:75]
	v_pk_fma_f32 v[74:75], v[56:57], v[74:75], v[56:57] neg_lo:[1,0,0] neg_hi:[1,0,0]
	v_pk_mul_f32 v[88:89], v[88:89], s[80:81] op_sel_hi:[1,0]
	v_cndmask_b32_e32 v74, v74, v90, vcc
	v_cmp_gt_f32_e32 vcc, 0, v57
	v_exp_f32_e32 v88, v88
	v_exp_f32_e32 v89, v89
	v_cndmask_b32_e32 v75, v75, v91, vcc
	v_pk_fma_f32 v[90:91], v[92:93], s[70:71], v[112:113] op_sel_hi:[1,0,0]
	v_cmp_gt_f32_e32 vcc, 0, v58
	v_pk_fma_f32 v[90:91], v[92:93], v[90:91], s[74:75] op_sel_hi:[1,1,0]
	v_pk_mul_f32 v[94:95], v[52:53], v[52:53]
	v_pk_fma_f32 v[90:91], v[92:93], v[90:91], s[76:77] op_sel_hi:[1,1,0]
	v_pk_mul_f32 v[94:95], v[94:95], s[80:81] op_sel_hi:[1,0]
	v_pk_fma_f32 v[90:91], v[92:93], v[90:91], s[78:79] op_sel_hi:[1,1,0]
	v_exp_f32_e32 v94, v94
	v_pk_mul_f32 v[90:91], v[92:93], v[90:91]
	v_and_b32_e32 v93, 0x7fffffff, v53
	v_and_b32_e32 v92, 0x7fffffff, v52
	v_pk_fma_f32 v[92:93], v[92:93], s[68:69], 1.0 op_sel_hi:[1,0,0]
	v_pk_mul_f32 v[88:89], v[88:89], v[90:91]
	v_rcp_f32_e32 v92, v92
	v_rcp_f32_e32 v93, v93
	v_pk_mul_f32 v[90:91], v[58:59], v[88:89]
	v_pk_fma_f32 v[88:89], v[58:59], v[88:89], v[58:59] neg_lo:[1,0,0] neg_hi:[1,0,0]
	v_exp_f32_e32 v95, v95
	v_cndmask_b32_e32 v88, v88, v90, vcc
	v_cmp_gt_f32_e32 vcc, 0, v59
	v_and_b32_e32 v115, 0x7fffffff, v55
	v_and_b32_e32 v114, 0x7fffffff, v54
	v_cndmask_b32_e32 v89, v89, v91, vcc
	v_pk_fma_f32 v[90:91], v[92:93], s[70:71], v[112:113] op_sel_hi:[1,0,0]
	v_pk_fma_f32 v[114:115], v[114:115], s[68:69], 1.0 op_sel_hi:[1,0,0]
	v_pk_fma_f32 v[90:91], v[92:93], v[90:91], s[74:75] op_sel_hi:[1,1,0]
	v_rcp_f32_e32 v114, v114
	v_pk_fma_f32 v[90:91], v[92:93], v[90:91], s[76:77] op_sel_hi:[1,1,0]
	v_rcp_f32_e32 v115, v115
	v_pk_fma_f32 v[90:91], v[92:93], v[90:91], s[78:79] op_sel_hi:[1,1,0]
	v_cmp_gt_f32_e32 vcc, 0, v52
	v_pk_mul_f32 v[90:91], v[92:93], v[90:91]
	v_pk_mul_f32 v[92:93], v[54:55], v[54:55]
	v_pk_mul_f32 v[90:91], v[94:95], v[90:91]
	v_pk_mul_f32 v[92:93], v[92:93], s[80:81] op_sel_hi:[1,0]
	v_pk_mul_f32 v[94:95], v[52:53], v[90:91]
	v_pk_fma_f32 v[90:91], v[52:53], v[90:91], v[52:53] neg_lo:[1,0,0] neg_hi:[1,0,0]
	v_exp_f32_e32 v92, v92
	v_cndmask_b32_e32 v90, v90, v94, vcc
	v_cmp_gt_f32_e32 vcc, 0, v53
	v_exp_f32_e32 v93, v93
	s_waitcnt vmcnt(8)
	v_and_b32_e32 v119, 0x7fffffff, v51
	v_cndmask_b32_e32 v91, v91, v95, vcc
	v_pk_fma_f32 v[94:95], v[114:115], s[70:71], v[112:113] op_sel_hi:[1,0,0]
	v_cmp_gt_f32_e32 vcc, 0, v54
	v_pk_fma_f32 v[94:95], v[114:115], v[94:95], s[74:75] op_sel_hi:[1,1,0]
	v_and_b32_e32 v118, 0x7fffffff, v50
	v_pk_fma_f32 v[94:95], v[114:115], v[94:95], s[76:77] op_sel_hi:[1,1,0]
	v_pk_fma_f32 v[118:119], v[118:119], s[68:69], 1.0 op_sel_hi:[1,0,0]
	v_pk_fma_f32 v[94:95], v[114:115], v[94:95], s[78:79] op_sel_hi:[1,1,0]
	v_rcp_f32_e32 v118, v118
	v_pk_mul_f32 v[94:95], v[114:115], v[94:95]
	v_and_b32_e32 v115, 0x7fffffff, v49
	v_and_b32_e32 v114, 0x7fffffff, v48
	v_pk_fma_f32 v[114:115], v[114:115], s[68:69], 1.0 op_sel_hi:[1,0,0]
	v_pk_mul_f32 v[92:93], v[92:93], v[94:95]
	v_rcp_f32_e32 v114, v114
	v_rcp_f32_e32 v115, v115
	v_pk_mul_f32 v[94:95], v[54:55], v[92:93]
	v_pk_fma_f32 v[92:93], v[54:55], v[92:93], v[54:55] neg_lo:[1,0,0] neg_hi:[1,0,0]
	v_rcp_f32_e32 v119, v119
	v_cndmask_b32_e32 v92, v92, v94, vcc
	v_cmp_gt_f32_e32 vcc, 0, v55
	v_pk_mul_f32 v[116:117], v[48:49], v[48:49]
	s_nop 0
	v_cndmask_b32_e32 v93, v93, v95, vcc
	v_pk_fma_f32 v[94:95], v[114:115], s[70:71], v[112:113] op_sel_hi:[1,0,0]
	v_pk_mul_f32 v[116:117], v[116:117], s[80:81] op_sel_hi:[1,0]
	v_pk_fma_f32 v[94:95], v[114:115], v[94:95], s[74:75] op_sel_hi:[1,1,0]
	v_exp_f32_e32 v116, v116
	v_pk_fma_f32 v[94:95], v[114:115], v[94:95], s[76:77] op_sel_hi:[1,1,0]
	v_exp_f32_e32 v117, v117
	v_pk_fma_f32 v[94:95], v[114:115], v[94:95], s[78:79] op_sel_hi:[1,1,0]
	v_pk_fma_f32 v[112:113], v[118:119], s[70:71], v[112:113] op_sel_hi:[1,0,0]
	v_pk_mul_f32 v[94:95], v[114:115], v[94:95]
	v_pk_mul_f32 v[114:115], v[50:51], v[50:51]
	v_pk_fma_f32 v[112:113], v[118:119], v[112:113], s[74:75] op_sel_hi:[1,1,0]
	v_pk_mul_f32 v[114:115], v[114:115], s[80:81] op_sel_hi:[1,0]
	v_pk_fma_f32 v[112:113], v[118:119], v[112:113], s[76:77] op_sel_hi:[1,1,0]
	v_exp_f32_e32 v114, v114
	v_exp_f32_e32 v115, v115
	v_pk_mul_f32 v[94:95], v[116:117], v[94:95]
	v_pk_fma_f32 v[112:113], v[118:119], v[112:113], s[78:79] op_sel_hi:[1,1,0]
	v_pk_mul_f32 v[116:117], v[48:49], v[94:95]
	v_pk_fma_f32 v[94:95], v[48:49], v[94:95], v[48:49] neg_lo:[1,0,0] neg_hi:[1,0,0]
	v_cmp_gt_f32_e32 vcc, 0, v48
	v_pk_mul_f32 v[112:113], v[118:119], v[112:113]
	s_nop 0
	v_cndmask_b32_e32 v94, v94, v116, vcc
	v_cmp_gt_f32_e32 vcc, 0, v49
	v_pk_mul_f32 v[112:113], v[114:115], v[112:113]
	v_mul_f32_e32 v116, v71, v71
	v_cndmask_b32_e32 v95, v95, v117, vcc
	v_pk_mul_f32 v[114:115], v[50:51], v[112:113]
	v_pk_fma_f32 v[112:113], v[50:51], v[112:113], v[50:51] neg_lo:[1,0,0] neg_hi:[1,0,0]
	v_cmp_gt_f32_e32 vcc, 0, v50
	v_fmac_f32_e32 v116, v70, v70
	v_fmac_f32_e32 v116, v72, v72
	v_cndmask_b32_e32 v112, v112, v114, vcc
	v_add_f32_e32 v114, 0, v70
	v_add_f32_e32 v114, v71, v114
	v_add_f32_e32 v114, v72, v114
	v_add_f32_e32 v114, v73, v114
	v_add_f32_e32 v114, v74, v114
	v_add_f32_e32 v114, v75, v114
	v_fmac_f32_e32 v116, v73, v73
	v_add_f32_e32 v114, v88, v114
	v_fmac_f32_e32 v116, v74, v74
	v_add_f32_e32 v114, v89, v114
	v_fmac_f32_e32 v116, v75, v75
	v_add_f32_e32 v114, v90, v114
	v_fmac_f32_e32 v116, v88, v88
	v_add_f32_e32 v114, v91, v114
	v_fmac_f32_e32 v116, v89, v89
	v_add_f32_e32 v114, v92, v114
	v_cmp_gt_f32_e32 vcc, 0, v51
	v_fmac_f32_e32 v116, v90, v90
	v_add_f32_e32 v114, v93, v114
	v_and_b32_e32 v117, 64, v229
	v_cndmask_b32_e32 v113, v113, v115, vcc
	v_fmac_f32_e32 v116, v91, v91
	v_add_f32_e32 v114, v94, v114
	v_xor_b32_e32 v115, 16, v229
	v_add_u32_e32 v117, 64, v117
	v_fmac_f32_e32 v116, v92, v92
	v_add_f32_e32 v114, v95, v114
	v_cmp_lt_i32_e32 vcc, v115, v117
	v_fmac_f32_e32 v116, v93, v93
	v_add_f32_e32 v114, v112, v114
	v_cndmask_b32_e32 v115, v229, v115, vcc
	v_add_f32_e32 v114, v113, v114
	v_lshlrev_b32_e32 v115, 2, v115
	v_fmac_f32_e32 v116, v94, v94
	v_mov_b32_e32 v118, v114
	s_nop 1
	v_permlane16_swap_b32_e32 v114, v118
	s_nop 1
	v_fmac_f32_e32 v116, v95, v95
	v_fmac_f32_e32 v116, v112, v112
	v_fmac_f32_e32 v116, v113, v113
	v_mov_b32_e32 v119, v116
	s_nop 1
	v_permlane16_swap_b32_e32 v116, v119
	s_nop 1
	s_waitcnt lgkmcnt(1)
	v_add_f32_e32 v114, v114, v118
	v_xor_b32_e32 v118, 32, v229
	v_cmp_lt_i32_e32 vcc, v118, v117
	s_waitcnt lgkmcnt(0)
	v_add_f32_e32 v116, v116, v119
	v_cndmask_b32_e32 v115, v229, v118, vcc
	v_lshlrev_b32_e32 v117, 2, v115
	v_mov_b32_e32 v115, v114
	s_nop 1
	v_permlane32_swap_b32_e32 v114, v115
	s_nop 1
	v_mov_b32_e32 v117, v116
	s_nop 1
	v_permlane32_swap_b32_e32 v116, v117
	s_nop 1
	s_and_saveexec_b64 s[90:91], s[4:5]
	s_cbranch_execz .LBB0_615
	v_lshlrev_b64 v[118:119], 2, v[68:69]
	s_waitcnt vmcnt(7)
	v_lshl_add_u64 v[120:121], s[14:15], 0, v[118:119]
	v_lshl_add_u64 v[118:119], s[52:53], 0, v[118:119]
	s_waitcnt lgkmcnt(1)
	v_add_f32_e32 v114, v114, v115
	s_waitcnt lgkmcnt(0)
	v_add_f32_e32 v115, v116, v117
	global_atomic_add_f32 v[118:119], v114, off
	global_atomic_add_f32 v[120:121], v115, off

.LBB0_621:
	s_nop 0
	v_fmamk_f32 v48, v234, 0x3a800000, v228
	v_rsq_f32_e32 v50, v48
	v_add_u32_e32 v48, 0xa0, v198
	v_ashrrev_i32_e32 v49, 31, v48
	s_and_b64 vcc, exec, s[10:11]
	v_pk_fma_f32 v[30:31], v[30:31], v[50:51], v[46:47] op_sel_hi:[1,0,1]
	v_pk_fma_f32 v[28:29], v[28:29], v[50:51], v[44:45] op_sel_hi:[1,0,1]
	v_pk_fma_f32 v[26:27], v[26:27], v[50:51], v[42:43] op_sel_hi:[1,0,1]
	v_pk_fma_f32 v[24:25], v[24:25], v[50:51], v[40:41] op_sel_hi:[1,0,1]
	v_pk_fma_f32 v[22:23], v[22:23], v[50:51], v[38:39] op_sel_hi:[1,0,1]
	v_pk_fma_f32 v[20:21], v[20:21], v[50:51], v[36:37] op_sel_hi:[1,0,1]
	v_pk_fma_f32 v[18:19], v[18:19], v[50:51], v[34:35] op_sel_hi:[1,0,1]
	v_pk_fma_f32 v[16:17], v[16:17], v[50:51], v[32:33] op_sel_hi:[1,0,1]
	s_mov_b64 s[12:13], -1
	s_cbranch_vccnz .LBB0_627
	s_and_b64 vcc, exec, s[8:9]
	v_mov_b32_e32 v53, v31
	v_mov_b32_e32 v52, v30
	v_mov_b32_e32 v51, v29
	v_mov_b32_e32 v50, v28
	v_mov_b32_e32 v57, v27
	v_mov_b32_e32 v56, v26
	v_mov_b32_e32 v55, v25
	v_mov_b32_e32 v54, v24
	v_mov_b32_e32 v61, v23
	v_mov_b32_e32 v60, v22
	v_mov_b32_e32 v59, v21
	v_mov_b32_e32 v58, v20
	s_waitcnt vmcnt(7)
	v_mov_b32_e32 v65, v19
	v_mov_b32_e32 v64, v18
	v_mov_b32_e32 v63, v17
	v_mov_b32_e32 v62, v16
	s_cbranch_vccnz .LBB0_626
	v_and_b32_e32 v51, 0x7fffffff, v29
	v_and_b32_e32 v50, 0x7fffffff, v28
	v_pk_fma_f32 v[50:51], v[50:51], s[68:69], 1.0 op_sel_hi:[1,0,0]
	v_mov_b64_e32 v[64:65], s[72:73]
	v_rcp_f32_e32 v50, v50
	v_rcp_f32_e32 v51, v51
	v_pk_mul_f32 v[54:55], v[28:29], v[28:29]
	v_and_b32_e32 v57, 0x7fffffff, v31
	v_pk_mul_f32 v[54:55], v[54:55], s[80:81] op_sel_hi:[1,0]
	v_pk_fma_f32 v[52:53], v[50:51], s[70:71], v[64:65] op_sel_hi:[1,0,0]
	v_exp_f32_e32 v54, v54
	v_pk_fma_f32 v[52:53], v[50:51], v[52:53], s[74:75] op_sel_hi:[1,1,0]
	v_exp_f32_e32 v55, v55
	v_pk_fma_f32 v[52:53], v[50:51], v[52:53], s[76:77] op_sel_hi:[1,1,0]
	v_and_b32_e32 v56, 0x7fffffff, v30
	v_pk_fma_f32 v[52:53], v[50:51], v[52:53], s[78:79] op_sel_hi:[1,1,0]
	v_pk_fma_f32 v[56:57], v[56:57], s[68:69], 1.0 op_sel_hi:[1,0,0]
	v_pk_mul_f32 v[50:51], v[50:51], v[52:53]
	v_rcp_f32_e32 v56, v56
	v_rcp_f32_e32 v57, v57
	v_pk_mul_f32 v[50:51], v[54:55], v[50:51]
	v_cmp_gt_f32_e32 vcc, 0, v28
	v_pk_mul_f32 v[54:55], v[28:29], v[50:51]
	v_pk_fma_f32 v[50:51], v[28:29], v[50:51], v[28:29] neg_lo:[1,0,0] neg_hi:[1,0,0]
	v_pk_mul_f32 v[52:53], v[30:31], v[30:31]
	v_cndmask_b32_e32 v50, v50, v54, vcc
	v_cmp_gt_f32_e32 vcc, 0, v29
	v_pk_mul_f32 v[52:53], v[52:53], s[80:81] op_sel_hi:[1,0]
	v_pk_mul_f32 v[58:59], v[24:25], v[24:25]
	v_cndmask_b32_e32 v51, v51, v55, vcc
	v_pk_fma_f32 v[54:55], v[56:57], s[70:71], v[64:65] op_sel_hi:[1,0,0]
	v_exp_f32_e32 v52, v52
	v_pk_fma_f32 v[54:55], v[56:57], v[54:55], s[74:75] op_sel_hi:[1,1,0]
	v_exp_f32_e32 v53, v53
	v_pk_fma_f32 v[54:55], v[56:57], v[54:55], s[76:77] op_sel_hi:[1,1,0]
	v_cmp_gt_f32_e32 vcc, 0, v30
	v_pk_fma_f32 v[54:55], v[56:57], v[54:55], s[78:79] op_sel_hi:[1,1,0]
	v_pk_mul_f32 v[58:59], v[58:59], s[80:81] op_sel_hi:[1,0]
	v_pk_mul_f32 v[54:55], v[56:57], v[54:55]
	v_and_b32_e32 v57, 0x7fffffff, v25
	v_and_b32_e32 v56, 0x7fffffff, v24
	v_pk_fma_f32 v[56:57], v[56:57], s[68:69], 1.0 op_sel_hi:[1,0,0]
	v_pk_mul_f32 v[52:53], v[52:53], v[54:55]
	v_rcp_f32_e32 v56, v56
	v_rcp_f32_e32 v57, v57
	v_pk_mul_f32 v[54:55], v[30:31], v[52:53]
	v_pk_fma_f32 v[52:53], v[30:31], v[52:53], v[30:31] neg_lo:[1,0,0] neg_hi:[1,0,0]
	v_exp_f32_e32 v58, v58
	v_cndmask_b32_e32 v52, v52, v54, vcc
	v_cmp_gt_f32_e32 vcc, 0, v31
	v_exp_f32_e32 v59, v59
	v_and_b32_e32 v61, 0x7fffffff, v27
	v_cndmask_b32_e32 v53, v53, v55, vcc
	v_pk_fma_f32 v[54:55], v[56:57], s[70:71], v[64:65] op_sel_hi:[1,0,0]
	v_and_b32_e32 v60, 0x7fffffff, v26
	v_pk_fma_f32 v[54:55], v[56:57], v[54:55], s[74:75] op_sel_hi:[1,1,0]
	v_pk_fma_f32 v[60:61], v[60:61], s[68:69], 1.0 op_sel_hi:[1,0,0]
	v_pk_fma_f32 v[54:55], v[56:57], v[54:55], s[76:77] op_sel_hi:[1,1,0]
	v_rcp_f32_e32 v60, v60
	v_pk_fma_f32 v[54:55], v[56:57], v[54:55], s[78:79] op_sel_hi:[1,1,0]
	v_rcp_f32_e32 v61, v61
	v_pk_mul_f32 v[54:55], v[56:57], v[54:55]
	v_cmp_gt_f32_e32 vcc, 0, v24
	v_pk_mul_f32 v[54:55], v[58:59], v[54:55]
	v_pk_mul_f32 v[56:57], v[26:27], v[26:27]
	v_pk_mul_f32 v[58:59], v[24:25], v[54:55]
	v_pk_fma_f32 v[54:55], v[24:25], v[54:55], v[24:25] neg_lo:[1,0,0] neg_hi:[1,0,0]
	v_pk_mul_f32 v[56:57], v[56:57], s[80:81] op_sel_hi:[1,0]
	v_cndmask_b32_e32 v54, v54, v58, vcc
	v_cmp_gt_f32_e32 vcc, 0, v25
	v_exp_f32_e32 v56, v56
	v_exp_f32_e32 v57, v57
	v_cndmask_b32_e32 v55, v55, v59, vcc
	v_pk_fma_f32 v[58:59], v[60:61], s[70:71], v[64:65] op_sel_hi:[1,0,0]
	v_cmp_gt_f32_e32 vcc, 0, v26
	v_pk_fma_f32 v[58:59], v[60:61], v[58:59], s[74:75] op_sel_hi:[1,1,0]
	v_pk_mul_f32 v[62:63], v[20:21], v[20:21]
	v_pk_fma_f32 v[58:59], v[60:61], v[58:59], s[76:77] op_sel_hi:[1,1,0]
	v_pk_mul_f32 v[62:63], v[62:63], s[80:81] op_sel_hi:[1,0]
	v_pk_fma_f32 v[58:59], v[60:61], v[58:59], s[78:79] op_sel_hi:[1,1,0]
	v_exp_f32_e32 v62, v62
	v_pk_mul_f32 v[58:59], v[60:61], v[58:59]
	v_and_b32_e32 v61, 0x7fffffff, v21
	v_and_b32_e32 v60, 0x7fffffff, v20
	v_pk_fma_f32 v[60:61], v[60:61], s[68:69], 1.0 op_sel_hi:[1,0,0]
	v_pk_mul_f32 v[56:57], v[56:57], v[58:59]
	v_rcp_f32_e32 v60, v60
	v_rcp_f32_e32 v61, v61
	v_pk_mul_f32 v[58:59], v[26:27], v[56:57]
	v_pk_fma_f32 v[56:57], v[26:27], v[56:57], v[26:27] neg_lo:[1,0,0] neg_hi:[1,0,0]
	v_exp_f32_e32 v63, v63
	v_cndmask_b32_e32 v56, v56, v58, vcc
	v_cmp_gt_f32_e32 vcc, 0, v27
	v_and_b32_e32 v67, 0x7fffffff, v23
	v_and_b32_e32 v66, 0x7fffffff, v22
	v_cndmask_b32_e32 v57, v57, v59, vcc
	v_pk_fma_f32 v[58:59], v[60:61], s[70:71], v[64:65] op_sel_hi:[1,0,0]
	v_pk_fma_f32 v[66:67], v[66:67], s[68:69], 1.0 op_sel_hi:[1,0,0]
	v_pk_fma_f32 v[58:59], v[60:61], v[58:59], s[74:75] op_sel_hi:[1,1,0]
	v_rcp_f32_e32 v66, v66
	v_pk_fma_f32 v[58:59], v[60:61], v[58:59], s[76:77] op_sel_hi:[1,1,0]
	v_rcp_f32_e32 v67, v67
	v_pk_fma_f32 v[58:59], v[60:61], v[58:59], s[78:79] op_sel_hi:[1,1,0]
	v_cmp_gt_f32_e32 vcc, 0, v20
	v_pk_mul_f32 v[58:59], v[60:61], v[58:59]
	v_pk_mul_f32 v[60:61], v[22:23], v[22:23]
	v_pk_mul_f32 v[58:59], v[62:63], v[58:59]
	v_pk_mul_f32 v[60:61], v[60:61], s[80:81] op_sel_hi:[1,0]
	v_pk_mul_f32 v[62:63], v[20:21], v[58:59]
	v_pk_fma_f32 v[58:59], v[20:21], v[58:59], v[20:21] neg_lo:[1,0,0] neg_hi:[1,0,0]
	v_exp_f32_e32 v60, v60
	v_cndmask_b32_e32 v58, v58, v62, vcc
	v_cmp_gt_f32_e32 vcc, 0, v21
	v_exp_f32_e32 v61, v61
	v_and_b32_e32 v71, 0x7fffffff, v19
	v_cndmask_b32_e32 v59, v59, v63, vcc
	v_pk_fma_f32 v[62:63], v[66:67], s[70:71], v[64:65] op_sel_hi:[1,0,0]
	v_cmp_gt_f32_e32 vcc, 0, v22
	v_pk_fma_f32 v[62:63], v[66:67], v[62:63], s[74:75] op_sel_hi:[1,1,0]
	v_and_b32_e32 v70, 0x7fffffff, v18
	v_pk_fma_f32 v[62:63], v[66:67], v[62:63], s[76:77] op_sel_hi:[1,1,0]
	v_pk_fma_f32 v[70:71], v[70:71], s[68:69], 1.0 op_sel_hi:[1,0,0]
	v_pk_fma_f32 v[62:63], v[66:67], v[62:63], s[78:79] op_sel_hi:[1,1,0]
	v_rcp_f32_e32 v70, v70
	v_pk_mul_f32 v[62:63], v[66:67], v[62:63]
	v_and_b32_e32 v67, 0x7fffffff, v17
	v_and_b32_e32 v66, 0x7fffffff, v16
	v_pk_fma_f32 v[66:67], v[66:67], s[68:69], 1.0 op_sel_hi:[1,0,0]
	v_pk_mul_f32 v[60:61], v[60:61], v[62:63]
	v_rcp_f32_e32 v66, v66
	v_rcp_f32_e32 v67, v67
	v_pk_mul_f32 v[62:63], v[22:23], v[60:61]
	v_pk_fma_f32 v[60:61], v[22:23], v[60:61], v[22:23] neg_lo:[1,0,0] neg_hi:[1,0,0]
	v_rcp_f32_e32 v71, v71
	v_cndmask_b32_e32 v60, v60, v62, vcc
	v_cmp_gt_f32_e32 vcc, 0, v23
	v_pk_mul_f32 v[68:69], v[16:17], v[16:17]
	s_nop 0
	v_cndmask_b32_e32 v61, v61, v63, vcc
	v_pk_fma_f32 v[62:63], v[66:67], s[70:71], v[64:65] op_sel_hi:[1,0,0]
	v_pk_mul_f32 v[68:69], v[68:69], s[80:81] op_sel_hi:[1,0]
	v_pk_fma_f32 v[62:63], v[66:67], v[62:63], s[74:75] op_sel_hi:[1,1,0]
	v_exp_f32_e32 v68, v68
	v_pk_fma_f32 v[62:63], v[66:67], v[62:63], s[76:77] op_sel_hi:[1,1,0]
	v_exp_f32_e32 v69, v69
	v_pk_fma_f32 v[62:63], v[66:67], v[62:63], s[78:79] op_sel_hi:[1,1,0]
	v_pk_fma_f32 v[64:65], v[70:71], s[70:71], v[64:65] op_sel_hi:[1,0,0]
	v_pk_mul_f32 v[62:63], v[66:67], v[62:63]
	v_pk_mul_f32 v[66:67], v[18:19], v[18:19]
	v_pk_fma_f32 v[64:65], v[70:71], v[64:65], s[74:75] op_sel_hi:[1,1,0]
	v_pk_mul_f32 v[66:67], v[66:67], s[80:81] op_sel_hi:[1,0]
	v_pk_fma_f32 v[64:65], v[70:71], v[64:65], s[76:77] op_sel_hi:[1,1,0]
	v_exp_f32_e32 v66, v66
	v_exp_f32_e32 v67, v67
	v_pk_mul_f32 v[62:63], v[68:69], v[62:63]
	v_pk_fma_f32 v[64:65], v[70:71], v[64:65], s[78:79] op_sel_hi:[1,1,0]
	v_pk_mul_f32 v[68:69], v[16:17], v[62:63]
	v_pk_fma_f32 v[62:63], v[16:17], v[62:63], v[16:17] neg_lo:[1,0,0] neg_hi:[1,0,0]
	v_cmp_gt_f32_e32 vcc, 0, v16
	v_pk_mul_f32 v[64:65], v[70:71], v[64:65]
	s_nop 0
	v_cndmask_b32_e32 v62, v62, v68, vcc
	v_cmp_gt_f32_e32 vcc, 0, v17
	v_pk_mul_f32 v[64:65], v[66:67], v[64:65]
	v_mul_f32_e32 v68, v51, v51
	v_cndmask_b32_e32 v63, v63, v69, vcc
	v_pk_mul_f32 v[66:67], v[18:19], v[64:65]
	v_pk_fma_f32 v[64:65], v[18:19], v[64:65], v[18:19] neg_lo:[1,0,0] neg_hi:[1,0,0]
	v_cmp_gt_f32_e32 vcc, 0, v18
	v_fmac_f32_e32 v68, v50, v50
	v_fmac_f32_e32 v68, v52, v52
	v_cndmask_b32_e32 v64, v64, v66, vcc
	v_add_f32_e32 v66, 0, v50
	v_add_f32_e32 v66, v51, v66
	v_add_f32_e32 v66, v52, v66
	v_add_f32_e32 v66, v53, v66
	v_add_f32_e32 v66, v54, v66
	v_add_f32_e32 v66, v55, v66
	v_fmac_f32_e32 v68, v53, v53
	v_add_f32_e32 v66, v56, v66
	v_fmac_f32_e32 v68, v54, v54
	v_add_f32_e32 v66, v57, v66
	v_fmac_f32_e32 v68, v55, v55
	v_add_f32_e32 v66, v58, v66
	v_fmac_f32_e32 v68, v56, v56
	v_add_f32_e32 v66, v59, v66
	v_fmac_f32_e32 v68, v57, v57
	v_add_f32_e32 v66, v60, v66
	v_cmp_gt_f32_e32 vcc, 0, v19
	v_fmac_f32_e32 v68, v58, v58
	v_add_f32_e32 v66, v61, v66
	v_and_b32_e32 v69, 64, v229
	v_cndmask_b32_e32 v65, v65, v67, vcc
	v_fmac_f32_e32 v68, v59, v59
	v_add_f32_e32 v66, v62, v66
	v_xor_b32_e32 v67, 16, v229
	v_add_u32_e32 v69, 64, v69
	v_fmac_f32_e32 v68, v60, v60
	v_add_f32_e32 v66, v63, v66
	v_cmp_lt_i32_e32 vcc, v67, v69
	v_fmac_f32_e32 v68, v61, v61
	v_add_f32_e32 v66, v64, v66
	v_cndmask_b32_e32 v67, v229, v67, vcc
	v_add_f32_e32 v66, v65, v66
	v_lshlrev_b32_e32 v67, 2, v67
	v_fmac_f32_e32 v68, v62, v62
	v_mov_b32_e32 v70, v66
	s_nop 1
	v_permlane16_swap_b32_e32 v66, v70
	s_nop 1
	v_fmac_f32_e32 v68, v63, v63
	v_fmac_f32_e32 v68, v64, v64
	v_fmac_f32_e32 v68, v65, v65
	v_mov_b32_e32 v71, v68
	s_nop 1
	v_permlane16_swap_b32_e32 v68, v71
	s_nop 1
	s_waitcnt lgkmcnt(1)
	v_add_f32_e32 v66, v66, v70
	v_xor_b32_e32 v70, 32, v229
	v_cmp_lt_i32_e32 vcc, v70, v69
	s_waitcnt lgkmcnt(0)
	v_add_f32_e32 v68, v68, v71
	v_cndmask_b32_e32 v67, v229, v70, vcc
	v_lshlrev_b32_e32 v69, 2, v67
	v_mov_b32_e32 v67, v66
	s_nop 1
	v_permlane32_swap_b32_e32 v66, v67
	s_nop 1
	v_mov_b32_e32 v69, v68
	s_nop 1
	v_permlane32_swap_b32_e32 v68, v69
	s_nop 1
	s_and_saveexec_b64 s[12:13], s[4:5]
	s_cbranch_execz .LBB0_625
	v_lshlrev_b64 v[70:71], 2, v[48:49]
	v_lshl_add_u64 v[72:73], s[14:15], 0, v[70:71]
	v_lshl_add_u64 v[70:71], s[52:53], 0, v[70:71]
	s_waitcnt lgkmcnt(1)
	v_add_f32_e32 v66, v66, v67
	s_waitcnt lgkmcnt(0)
	v_add_f32_e32 v67, v68, v69
	global_atomic_add_f32 v[70:71], v66, off
	global_atomic_add_f32 v[72:73], v67, off

.LBB0_629:
	v_lshlrev_b64 v[18:19], 11, v[48:49]
	v_lshl_add_u64 v[22:23], v[202:203], 0, v[18:19]
	v_cvt_pk_bf16_f32 v18, v50, v51
	v_cvt_pk_bf16_f32 v19, v52, v53
	v_cvt_pk_bf16_f32 v20, v54, v55
	v_cvt_pk_bf16_f32 v21, v56, v57
	global_store_dwordx4 v[22:23], v[18:21], off
	v_add_u32_e32 v16, 0xb0, v198
	v_ashrrev_i32_e32 v17, 31, v16
	v_fmamk_f32 v20, v233, 0x3a800000, v228
	v_rsq_f32_e32 v24, v20
	v_cvt_pk_bf16_f32 v18, v58, v59
	v_cvt_pk_bf16_f32 v19, v60, v61
	v_cvt_pk_bf16_f32 v20, v62, v63
	s_waitcnt vmcnt(8)
	v_cvt_pk_bf16_f32 v21, v64, v65
	s_and_b64 vcc, exec, s[10:11]
	v_pk_fma_f32 v[14:15], v[14:15], v[24:25], v[46:47] op_sel_hi:[1,0,1]
	v_pk_fma_f32 v[12:13], v[12:13], v[24:25], v[44:45] op_sel_hi:[1,0,1]
	v_pk_fma_f32 v[10:11], v[10:11], v[24:25], v[42:43] op_sel_hi:[1,0,1]
	v_pk_fma_f32 v[8:9], v[8:9], v[24:25], v[40:41] op_sel_hi:[1,0,1]
	v_pk_fma_f32 v[6:7], v[6:7], v[24:25], v[38:39] op_sel_hi:[1,0,1]
	v_pk_fma_f32 v[4:5], v[4:5], v[24:25], v[36:37] op_sel_hi:[1,0,1]
	v_pk_fma_f32 v[2:3], v[2:3], v[24:25], v[34:35] op_sel_hi:[1,0,1]
	v_pk_fma_f32 v[0:1], v[0:1], v[24:25], v[32:33] op_sel_hi:[1,0,1]
	s_mov_b64 s[10:11], -1
	global_store_dwordx4 v[22:23], v[18:21], off offset:256
	s_cbranch_vccnz .LBB0_635
	s_and_b64 vcc, exec, s[8:9]
	v_mov_b32_e32 v21, v15
	v_mov_b32_e32 v20, v14
	v_mov_b32_e32 v19, v13
	v_mov_b32_e32 v18, v12
	v_mov_b32_e32 v25, v11
	v_mov_b32_e32 v24, v10
	v_mov_b32_e32 v23, v9
	v_mov_b32_e32 v22, v8
	v_mov_b32_e32 v29, v7
	v_mov_b32_e32 v28, v6
	v_mov_b32_e32 v27, v5
	v_mov_b32_e32 v26, v4
	v_mov_b32_e32 v33, v3
	v_mov_b32_e32 v32, v2
	v_mov_b32_e32 v31, v1
	v_mov_b32_e32 v30, v0
	s_cbranch_vccnz .LBB0_634
	v_and_b32_e32 v19, 0x7fffffff, v13
	v_and_b32_e32 v18, 0x7fffffff, v12
	v_pk_fma_f32 v[18:19], v[18:19], s[68:69], 1.0 op_sel_hi:[1,0,0]
	v_mov_b64_e32 v[32:33], s[72:73]
	v_rcp_f32_e32 v18, v18
	v_rcp_f32_e32 v19, v19
	v_pk_mul_f32 v[22:23], v[12:13], v[12:13]
	v_and_b32_e32 v25, 0x7fffffff, v15
	v_pk_mul_f32 v[22:23], v[22:23], s[80:81] op_sel_hi:[1,0]
	v_pk_fma_f32 v[20:21], v[18:19], s[70:71], v[32:33] op_sel_hi:[1,0,0]
	v_exp_f32_e32 v22, v22
	v_pk_fma_f32 v[20:21], v[18:19], v[20:21], s[74:75] op_sel_hi:[1,1,0]
	v_exp_f32_e32 v23, v23
	v_pk_fma_f32 v[20:21], v[18:19], v[20:21], s[76:77] op_sel_hi:[1,1,0]
	v_and_b32_e32 v24, 0x7fffffff, v14
	v_pk_fma_f32 v[20:21], v[18:19], v[20:21], s[78:79] op_sel_hi:[1,1,0]
	v_pk_fma_f32 v[24:25], v[24:25], s[68:69], 1.0 op_sel_hi:[1,0,0]
	v_pk_mul_f32 v[18:19], v[18:19], v[20:21]
	v_rcp_f32_e32 v24, v24
	v_rcp_f32_e32 v25, v25
	v_pk_mul_f32 v[18:19], v[22:23], v[18:19]
	v_cmp_gt_f32_e32 vcc, 0, v12
	v_pk_mul_f32 v[22:23], v[12:13], v[18:19]
	v_pk_fma_f32 v[18:19], v[12:13], v[18:19], v[12:13] neg_lo:[1,0,0] neg_hi:[1,0,0]
	v_pk_mul_f32 v[20:21], v[14:15], v[14:15]
	v_cndmask_b32_e32 v18, v18, v22, vcc
	v_cmp_gt_f32_e32 vcc, 0, v13
	v_pk_mul_f32 v[20:21], v[20:21], s[80:81] op_sel_hi:[1,0]
	v_pk_mul_f32 v[26:27], v[8:9], v[8:9]
	v_cndmask_b32_e32 v19, v19, v23, vcc
	v_pk_fma_f32 v[22:23], v[24:25], s[70:71], v[32:33] op_sel_hi:[1,0,0]
	v_exp_f32_e32 v20, v20
	v_pk_fma_f32 v[22:23], v[24:25], v[22:23], s[74:75] op_sel_hi:[1,1,0]
	v_exp_f32_e32 v21, v21
	v_pk_fma_f32 v[22:23], v[24:25], v[22:23], s[76:77] op_sel_hi:[1,1,0]
	v_cmp_gt_f32_e32 vcc, 0, v14
	v_pk_fma_f32 v[22:23], v[24:25], v[22:23], s[78:79] op_sel_hi:[1,1,0]
	v_pk_mul_f32 v[26:27], v[26:27], s[80:81] op_sel_hi:[1,0]
	v_pk_mul_f32 v[22:23], v[24:25], v[22:23]
	v_and_b32_e32 v25, 0x7fffffff, v9
	v_and_b32_e32 v24, 0x7fffffff, v8
	v_pk_fma_f32 v[24:25], v[24:25], s[68:69], 1.0 op_sel_hi:[1,0,0]
	v_pk_mul_f32 v[20:21], v[20:21], v[22:23]
	v_rcp_f32_e32 v24, v24
	v_rcp_f32_e32 v25, v25
	v_pk_mul_f32 v[22:23], v[14:15], v[20:21]
	v_pk_fma_f32 v[20:21], v[14:15], v[20:21], v[14:15] neg_lo:[1,0,0] neg_hi:[1,0,0]
	v_exp_f32_e32 v26, v26
	v_cndmask_b32_e32 v20, v20, v22, vcc
	v_cmp_gt_f32_e32 vcc, 0, v15
	v_exp_f32_e32 v27, v27
	v_and_b32_e32 v29, 0x7fffffff, v11
	v_cndmask_b32_e32 v21, v21, v23, vcc
	v_pk_fma_f32 v[22:23], v[24:25], s[70:71], v[32:33] op_sel_hi:[1,0,0]
	v_and_b32_e32 v28, 0x7fffffff, v10
	v_pk_fma_f32 v[22:23], v[24:25], v[22:23], s[74:75] op_sel_hi:[1,1,0]
	v_pk_fma_f32 v[28:29], v[28:29], s[68:69], 1.0 op_sel_hi:[1,0,0]
	v_pk_fma_f32 v[22:23], v[24:25], v[22:23], s[76:77] op_sel_hi:[1,1,0]
	v_rcp_f32_e32 v28, v28
	v_pk_fma_f32 v[22:23], v[24:25], v[22:23], s[78:79] op_sel_hi:[1,1,0]
	v_rcp_f32_e32 v29, v29
	v_pk_mul_f32 v[22:23], v[24:25], v[22:23]
	v_cmp_gt_f32_e32 vcc, 0, v8
	v_pk_mul_f32 v[22:23], v[26:27], v[22:23]
	v_pk_mul_f32 v[24:25], v[10:11], v[10:11]
	v_pk_mul_f32 v[26:27], v[8:9], v[22:23]
	v_pk_fma_f32 v[22:23], v[8:9], v[22:23], v[8:9] neg_lo:[1,0,0] neg_hi:[1,0,0]
	v_pk_mul_f32 v[24:25], v[24:25], s[80:81] op_sel_hi:[1,0]
	v_cndmask_b32_e32 v22, v22, v26, vcc
	v_cmp_gt_f32_e32 vcc, 0, v9
	v_exp_f32_e32 v24, v24
	v_exp_f32_e32 v25, v25
	v_cndmask_b32_e32 v23, v23, v27, vcc
	v_pk_fma_f32 v[26:27], v[28:29], s[70:71], v[32:33] op_sel_hi:[1,0,0]
	v_cmp_gt_f32_e32 vcc, 0, v10
	v_pk_fma_f32 v[26:27], v[28:29], v[26:27], s[74:75] op_sel_hi:[1,1,0]
	v_pk_mul_f32 v[30:31], v[4:5], v[4:5]
	v_pk_fma_f32 v[26:27], v[28:29], v[26:27], s[76:77] op_sel_hi:[1,1,0]
	v_pk_mul_f32 v[30:31], v[30:31], s[80:81] op_sel_hi:[1,0]
	v_pk_fma_f32 v[26:27], v[28:29], v[26:27], s[78:79] op_sel_hi:[1,1,0]
	v_exp_f32_e32 v30, v30
	v_pk_mul_f32 v[26:27], v[28:29], v[26:27]
	v_and_b32_e32 v29, 0x7fffffff, v5
	v_and_b32_e32 v28, 0x7fffffff, v4
	v_pk_fma_f32 v[28:29], v[28:29], s[68:69], 1.0 op_sel_hi:[1,0,0]
	v_pk_mul_f32 v[24:25], v[24:25], v[26:27]
	v_rcp_f32_e32 v28, v28
	v_rcp_f32_e32 v29, v29
	v_pk_mul_f32 v[26:27], v[10:11], v[24:25]
	v_pk_fma_f32 v[24:25], v[10:11], v[24:25], v[10:11] neg_lo:[1,0,0] neg_hi:[1,0,0]
	v_exp_f32_e32 v31, v31
	v_cndmask_b32_e32 v24, v24, v26, vcc
	v_cmp_gt_f32_e32 vcc, 0, v11
	v_and_b32_e32 v35, 0x7fffffff, v7
	v_and_b32_e32 v34, 0x7fffffff, v6
	v_cndmask_b32_e32 v25, v25, v27, vcc
	v_pk_fma_f32 v[26:27], v[28:29], s[70:71], v[32:33] op_sel_hi:[1,0,0]
	v_pk_fma_f32 v[34:35], v[34:35], s[68:69], 1.0 op_sel_hi:[1,0,0]
	v_pk_fma_f32 v[26:27], v[28:29], v[26:27], s[74:75] op_sel_hi:[1,1,0]
	v_rcp_f32_e32 v34, v34
	v_pk_fma_f32 v[26:27], v[28:29], v[26:27], s[76:77] op_sel_hi:[1,1,0]
	v_rcp_f32_e32 v35, v35
	v_pk_fma_f32 v[26:27], v[28:29], v[26:27], s[78:79] op_sel_hi:[1,1,0]
	v_cmp_gt_f32_e32 vcc, 0, v4
	v_pk_mul_f32 v[26:27], v[28:29], v[26:27]
	v_pk_mul_f32 v[28:29], v[6:7], v[6:7]
	v_pk_mul_f32 v[26:27], v[30:31], v[26:27]
	v_pk_mul_f32 v[28:29], v[28:29], s[80:81] op_sel_hi:[1,0]
	v_pk_mul_f32 v[30:31], v[4:5], v[26:27]
	v_pk_fma_f32 v[26:27], v[4:5], v[26:27], v[4:5] neg_lo:[1,0,0] neg_hi:[1,0,0]
	v_exp_f32_e32 v28, v28
	v_cndmask_b32_e32 v26, v26, v30, vcc
	v_cmp_gt_f32_e32 vcc, 0, v5
	v_exp_f32_e32 v29, v29
	v_and_b32_e32 v39, 0x7fffffff, v3
	v_cndmask_b32_e32 v27, v27, v31, vcc
	v_pk_fma_f32 v[30:31], v[34:35], s[70:71], v[32:33] op_sel_hi:[1,0,0]
	v_cmp_gt_f32_e32 vcc, 0, v6
	v_pk_fma_f32 v[30:31], v[34:35], v[30:31], s[74:75] op_sel_hi:[1,1,0]
	v_and_b32_e32 v38, 0x7fffffff, v2
	v_pk_fma_f32 v[30:31], v[34:35], v[30:31], s[76:77] op_sel_hi:[1,1,0]
	v_pk_fma_f32 v[38:39], v[38:39], s[68:69], 1.0 op_sel_hi:[1,0,0]
	v_pk_fma_f32 v[30:31], v[34:35], v[30:31], s[78:79] op_sel_hi:[1,1,0]
	v_rcp_f32_e32 v38, v38
	v_pk_mul_f32 v[30:31], v[34:35], v[30:31]
	v_and_b32_e32 v35, 0x7fffffff, v1
	v_and_b32_e32 v34, 0x7fffffff, v0
	v_pk_fma_f32 v[34:35], v[34:35], s[68:69], 1.0 op_sel_hi:[1,0,0]
	v_pk_mul_f32 v[28:29], v[28:29], v[30:31]
	v_rcp_f32_e32 v34, v34
	v_rcp_f32_e32 v35, v35
	v_pk_mul_f32 v[30:31], v[6:7], v[28:29]
	v_pk_fma_f32 v[28:29], v[6:7], v[28:29], v[6:7] neg_lo:[1,0,0] neg_hi:[1,0,0]
	v_rcp_f32_e32 v39, v39
	v_cndmask_b32_e32 v28, v28, v30, vcc
	v_cmp_gt_f32_e32 vcc, 0, v7
	v_pk_mul_f32 v[36:37], v[0:1], v[0:1]
	s_nop 0
	v_cndmask_b32_e32 v29, v29, v31, vcc
	v_pk_fma_f32 v[30:31], v[34:35], s[70:71], v[32:33] op_sel_hi:[1,0,0]
	v_pk_mul_f32 v[36:37], v[36:37], s[80:81] op_sel_hi:[1,0]
	v_pk_fma_f32 v[30:31], v[34:35], v[30:31], s[74:75] op_sel_hi:[1,1,0]
	v_exp_f32_e32 v36, v36
	v_pk_fma_f32 v[30:31], v[34:35], v[30:31], s[76:77] op_sel_hi:[1,1,0]
	v_exp_f32_e32 v37, v37
	v_pk_fma_f32 v[30:31], v[34:35], v[30:31], s[78:79] op_sel_hi:[1,1,0]
	v_pk_fma_f32 v[32:33], v[38:39], s[70:71], v[32:33] op_sel_hi:[1,0,0]
	v_pk_mul_f32 v[30:31], v[34:35], v[30:31]
	v_pk_mul_f32 v[34:35], v[2:3], v[2:3]
	v_pk_fma_f32 v[32:33], v[38:39], v[32:33], s[74:75] op_sel_hi:[1,1,0]
	v_pk_mul_f32 v[34:35], v[34:35], s[80:81] op_sel_hi:[1,0]
	v_pk_fma_f32 v[32:33], v[38:39], v[32:33], s[76:77] op_sel_hi:[1,1,0]
	v_exp_f32_e32 v34, v34
	v_exp_f32_e32 v35, v35
	v_pk_mul_f32 v[30:31], v[36:37], v[30:31]
	v_pk_fma_f32 v[32:33], v[38:39], v[32:33], s[78:79] op_sel_hi:[1,1,0]
	v_pk_mul_f32 v[36:37], v[0:1], v[30:31]
	v_pk_fma_f32 v[30:31], v[0:1], v[30:31], v[0:1] neg_lo:[1,0,0] neg_hi:[1,0,0]
	v_cmp_gt_f32_e32 vcc, 0, v0
	v_pk_mul_f32 v[32:33], v[38:39], v[32:33]
	s_nop 0
	v_cndmask_b32_e32 v30, v30, v36, vcc
	v_cmp_gt_f32_e32 vcc, 0, v1
	v_pk_mul_f32 v[32:33], v[34:35], v[32:33]
	v_mul_f32_e32 v36, v19, v19
	v_cndmask_b32_e32 v31, v31, v37, vcc
	v_pk_mul_f32 v[34:35], v[2:3], v[32:33]
	v_pk_fma_f32 v[32:33], v[2:3], v[32:33], v[2:3] neg_lo:[1,0,0] neg_hi:[1,0,0]
	v_cmp_gt_f32_e32 vcc, 0, v2
	v_fmac_f32_e32 v36, v18, v18
	v_fmac_f32_e32 v36, v20, v20
	v_cndmask_b32_e32 v32, v32, v34, vcc
	v_add_f32_e32 v34, 0, v18
	v_add_f32_e32 v34, v19, v34
	v_add_f32_e32 v34, v20, v34
	v_add_f32_e32 v34, v21, v34
	v_add_f32_e32 v34, v22, v34
	v_add_f32_e32 v34, v23, v34
	v_fmac_f32_e32 v36, v21, v21
	v_add_f32_e32 v34, v24, v34
	v_fmac_f32_e32 v36, v22, v22
	v_add_f32_e32 v34, v25, v34
	v_fmac_f32_e32 v36, v23, v23
	v_add_f32_e32 v34, v26, v34
	v_fmac_f32_e32 v36, v24, v24
	v_add_f32_e32 v34, v27, v34
	v_fmac_f32_e32 v36, v25, v25
	v_add_f32_e32 v34, v28, v34
	v_cmp_gt_f32_e32 vcc, 0, v3
	v_fmac_f32_e32 v36, v26, v26
	v_add_f32_e32 v34, v29, v34
	v_and_b32_e32 v37, 64, v229
	v_cndmask_b32_e32 v33, v33, v35, vcc
	v_fmac_f32_e32 v36, v27, v27
	v_add_f32_e32 v34, v30, v34
	v_xor_b32_e32 v35, 16, v229
	v_add_u32_e32 v37, 64, v37
	v_fmac_f32_e32 v36, v28, v28
	v_add_f32_e32 v34, v31, v34
	v_cmp_lt_i32_e32 vcc, v35, v37
	v_fmac_f32_e32 v36, v29, v29
	v_add_f32_e32 v34, v32, v34
	v_cndmask_b32_e32 v35, v229, v35, vcc
	v_add_f32_e32 v34, v33, v34
	v_lshlrev_b32_e32 v35, 2, v35
	v_fmac_f32_e32 v36, v30, v30
	v_mov_b32_e32 v38, v34
	s_nop 1
	v_permlane16_swap_b32_e32 v34, v38
	s_nop 1
	v_fmac_f32_e32 v36, v31, v31
	v_fmac_f32_e32 v36, v32, v32
	v_fmac_f32_e32 v36, v33, v33
	v_mov_b32_e32 v39, v36
	s_nop 1
	v_permlane16_swap_b32_e32 v36, v39
	s_nop 1
	s_waitcnt lgkmcnt(1)
	v_add_f32_e32 v34, v34, v38
	v_xor_b32_e32 v38, 32, v229
	v_cmp_lt_i32_e32 vcc, v38, v37
	s_waitcnt lgkmcnt(0)
	v_add_f32_e32 v36, v36, v39
	v_cndmask_b32_e32 v35, v229, v38, vcc
	v_lshlrev_b32_e32 v37, 2, v35
	v_mov_b32_e32 v35, v34
	s_nop 1
	v_permlane32_swap_b32_e32 v34, v35
	s_nop 1
	v_mov_b32_e32 v37, v36
	s_nop 1
	v_permlane32_swap_b32_e32 v36, v37
	s_nop 1
	s_and_saveexec_b64 s[8:9], s[4:5]
	s_cbranch_execz .LBB0_633
	v_lshlrev_b64 v[38:39], 2, v[16:17]
	v_lshl_add_u64 v[40:41], s[14:15], 0, v[38:39]
	v_lshl_add_u64 v[38:39], s[52:53], 0, v[38:39]
	s_waitcnt lgkmcnt(1)
	v_add_f32_e32 v34, v34, v35
	s_waitcnt lgkmcnt(0)
	v_add_f32_e32 v35, v36, v37
	global_atomic_add_f32 v[38:39], v34, off
	global_atomic_add_f32 v[40:41], v35, off
